# softmax serial chain trim (7.12): deleted 35 redundant canonicalizing v_max x,x in attention row-max chains, exact
# baseline (speedup 1.0000x reference)
; #define SWAIT() do { if constexpr (SDEPTH == 1) asm volatile("s_waitcnt vmcnt(0)" ::: "memory"); else if constexpr (MODE == 2) asm volatile("s_waitcnt vmcnt(5)" ::: "memory"); else asm volatile("s_waitcnt vmcnt(4)" ::: "memory"); } while (0)
; #define QKT(P0, P1, b, j) do { const bool v_ = VALID(j); qkt<MODE>(P0, P1, K_lds + (b) * SHM_K, K2_lds + (b) * SHM_K2, qr, Q2s, QHs, Q3s, r32, hi, v_); \
;     if constexpr (MODE == 1) { if (v_) { const bool far_ = ((qc0 - kc0) * 64 + wid * 32 - (j) * 64 - 63) >= 128; add_bias(P0, P1, tb, relq - (j) * 64, far_); } } } while (0)
; __device__ __forceinline__ void partialSM(f32x16& p0, f32x16& p1, float& m_reg, float& mn, float& alpha) {
;   float pmax = p0[0];
; #pragma unroll
;   for (int r = 1; r < 16; ++r) pmax = fmaxf(pmax, p0[r]);
; #pragma unroll
;   for (int r = 0; r < 16; ++r) pmax = fmaxf(pmax, p1[r]);
;   { auto rr = __builtin_amdgcn_permlane32_swap(__float_as_uint(pmax), __float_as_uint(pmax), false, false);
;     pmax = fmaxf(__uint_as_float(rr[0]), __uint_as_float(rr[1])); }
;   if (__builtin_expect(__all(pmax - m_reg <= THR), 1)) { mn = m_reg; alpha = 1.f; }
;   else { mn = fmaxf(m_reg, pmax); alpha = __builtin_amdgcn_exp2f(m_reg - mn); m_reg = mn; }
; template <int MODE> ...
;     ...
;   SLOAD(SE, 0); asm volatile("s_waitcnt vmcnt(0)" ::: "memory"); SWRITE(0, SE); __syncthreads();
;   QKT(pA0, pA1, 0, 0); partialSM(pA0, pA1, m_reg, mnA, alA);
;   SLOAD(SO, 1); if constexpr (SDEPTH == 2) { if (2 < NT) SLOAD(SE, 2); }
;   SWAIT(); SWRITE(1, SO); __syncthreads();
;   for (int j = 1; j + 1 < NT; j += 2) {
.LBB0_219:
	v_mov_b32_e32 v83, v175
	v_lshl_add_u64 v[2:3], v[84:85], 0, v[82:83]
	v_lshlrev_b64 v[2:3], 1, v[2:3]
	s_mov_b64 s[12:13], 0x90000
	v_lshl_add_u64 v[10:11], v[2:3], 0, s[12:13]
	s_mov_b64 s[12:13], 0xd8000
	v_lshl_add_u64 v[12:13], v[2:3], 0, s[12:13]
	v_lshl_add_u64 v[4:5], s[10:11], 0, v[10:11]
	v_lshl_add_u64 v[6:7], s[10:11], 0, v[12:13]
	v_lshl_add_u64 v[10:11], s[8:9], 0, v[10:11]
	global_load_dwordx4 v[2:5], v[4:5], off
	s_nop 0
	global_load_dwordx4 v[6:9], v[6:7], off
	v_lshl_add_u64 v[14:15], s[8:9], 0, v[12:13]
	global_load_dwordx4 v[10:13], v[10:11], off
	s_nop 0
	global_load_dwordx4 v[48:51], v[14:15], off
	v_and_b32_e32 v184, 63, v80
	v_lshlrev_b32_e32 v53, 4, v184
	v_lshlrev_b32_e32 v52, 3, v184
	v_and_b32_e32 v14, 0xc0, v53
	v_lshlrev_b32_e32 v15, 1, v184
	v_and_or_b32 v14, v52, 24, v14
	v_and_b32_e32 v15, 32, v15
	v_and_b32_e32 v52, 0x100, v52
	v_or3_b32 v197, v14, v15, v52
	v_max_f32_e32 v14, v32, v33
	v_max3_f32 v14, v14, v34, v35
	v_max3_f32 v14, v14, v36, v37
	v_max3_f32 v14, v14, v38, v39
	v_max3_f32 v14, v14, v40, v41
	v_max3_f32 v14, v14, v42, v43
	v_max3_f32 v14, v14, v44, v45
	v_max3_f32 v14, v14, v46, v47
	v_max3_f32 v14, v14, v16, v17
	v_max3_f32 v14, v14, v18, v19
	v_max3_f32 v14, v14, v20, v21
	v_max3_f32 v14, v14, v22, v23
	v_max3_f32 v14, v14, v24, v25
	v_max3_f32 v14, v14, v26, v27
	v_max3_f32 v14, v14, v28, v29
	v_max3_f32 v14, v14, v30, v31
	v_mov_b32_e32 v15, v14
	s_nop 1
	v_permlane32_swap_b32_e32 v14, v15
	s_cmp_lg_u32 0, -1
	s_cselect_b32 s8, 0, 0
	s_and_b32 s9, s18, 0x3fffffc0
	v_max_f32_e32 v14, v14, v15
	s_lshl_b32 s9, s9, 2
	v_add_f32_e32 v15, 0x7149f2ca, v14
	v_max_f32_e32 v14, 0xf149f2ca, v14
	s_add_i32 s9, s9, 0
	v_cmp_ge_f32_e32 vcc, s58, v15
	v_sub_f32_e32 v15, 0xf149f2ca, v14
	s_add_i32 s10, s19, 4
	s_add_i32 s9, s9, 0x10000
	s_add_i32 s11, s5, -8
	v_exp_f32_e32 v15, v15
	s_cmp_eq_u64 vcc, exec
	s_cselect_b64 vcc, -1, 0
	v_cndmask_b32_e32 v160, v14, v202, vcc
	v_cndmask_b32_e64 v194, v15, 1.0, vcc
	v_sub_f32_e32 v14, v32, v160
	v_sub_f32_e32 v15, v33, v160
	v_sub_f32_e32 v32, v34, v160
	v_sub_f32_e32 v33, v35, v160
	v_sub_f32_e32 v34, v36, v160
	v_sub_f32_e32 v35, v37, v160
	v_sub_f32_e32 v36, v38, v160
	v_sub_f32_e32 v37, v39, v160
	v_sub_f32_e32 v38, v40, v160
	v_sub_f32_e32 v39, v41, v160
	v_sub_f32_e32 v40, v42, v160
	v_sub_f32_e32 v41, v43, v160
	v_sub_f32_e32 v42, v44, v160
	v_sub_f32_e32 v43, v45, v160
	v_sub_f32_e32 v44, v46, v160
	v_sub_f32_e32 v45, v47, v160
	v_exp_f32_e32 v164, v14
	v_exp_f32_e32 v167, v15
	v_exp_f32_e32 v168, v32
	v_exp_f32_e32 v171, v33
	v_exp_f32_e32 v172, v34
	v_exp_f32_e32 v222, v35
	v_exp_f32_e32 v223, v36
	v_exp_f32_e32 v224, v37
	v_exp_f32_e32 v161, v38
	v_exp_f32_e32 v162, v39
	v_exp_f32_e32 v163, v40
	v_exp_f32_e32 v165, v41
	v_exp_f32_e32 v166, v42
	v_exp_f32_e32 v169, v43
	v_exp_f32_e32 v170, v44
	v_exp_f32_e32 v173, v45
	s_waitcnt vmcnt(0)
	v_sub_f32_e32 v97, v31, v160
	v_sub_f32_e32 v96, v30, v160
	v_sub_f32_e32 v99, v29, v160
	v_sub_f32_e32 v98, v28, v160
	v_sub_f32_e32 v101, v27, v160
	v_sub_f32_e32 v100, v26, v160
	v_sub_f32_e32 v103, v25, v160
	v_sub_f32_e32 v102, v24, v160
	v_sub_f32_e32 v105, v23, v160
	v_sub_f32_e32 v104, v22, v160
	v_sub_f32_e32 v107, v21, v160
	v_sub_f32_e32 v106, v20, v160
	v_sub_f32_e32 v109, v19, v160
	v_sub_f32_e32 v108, v18, v160
	v_sub_f32_e32 v111, v17, v160
	v_sub_f32_e32 v110, v16, v160
	s_cmp_lt_i32 s10, 3
	v_cmp_gt_u32_e64 s[36:37], 32, v184
	v_add_u32_e32 v208, s8, v197
	v_lshl_add_u32 v195, v183, 2, s9
	v_lshl_add_u32 v193, v1, 2, s9
	s_waitcnt vmcnt(3)
	ds_write_b128 v203, v[2:5] offset:16384
	s_waitcnt vmcnt(2)
	ds_write_b128 v204, v[6:9] offset:16384
	s_waitcnt vmcnt(1)
	ds_write_b128 v205, v[10:13] offset:49152
	s_waitcnt vmcnt(0)
	ds_write_b128 v206, v[48:51] offset:49152
	s_waitcnt lgkmcnt(0)
	s_barrier
	s_cbranch_scc1 .LBB0_250
	s_and_b32 s12, s14, 7
	s_lshr_b32 s9, s49, 7
	s_lshl_b32 s12, s12, 2
	s_add_i32 s12, s9, s12
	s_lshr_b32 s12, s12, 3
	s_mul_hi_u32 s18, s12, 0x2400000
	s_mul_i32 s19, s12, 0x2400000
	s_lshl_b32 s12, s14, 2
	s_add_i32 s12, s12, s9
	s_lshl_b32 s5, s54, 5
	s_and_b32 s9, s12, 7
	s_and_b32 s8, s5, 0xf00
	s_lshl_b32 s9, s9, 8
	s_cmp_lg_u32 0, -1
	v_or_b32_e32 v2, s8, v183
	s_cselect_b32 s12, 0, 0
	v_sub_u32_e32 v1, v2, v1
	s_sub_i32 s13, s8, s17
	s_or_b32 s8, s19, s9
	v_subrev_u32_e32 v219, s17, v1
	v_add_u32_e32 v1, s17, v81
	v_mov_b32_e32 v2, s8
	v_mov_b32_e32 v3, s18
	s_movk_i32 s8, 0x2400
	v_mad_i64_i32 v[2:3], s[8:9], v1, s8, v[2:3]
	v_and_b32_e32 v1, 15, v80
	v_readlane_b32 s8, v249, 20
	v_mov_b32_e32 v32, v175
	v_mov_b32_e32 v33, v175
	v_mov_b32_e32 v46, v175
	v_mov_b32_e32 v47, v175
	s_addk_i32 s12, 0x4000
	v_lshl_or_b32 v2, v1, 4, v2
	v_readlane_b32 s9, v249, 21
	v_mov_b32_e32 v34, v175
	v_mov_b32_e32 v35, v175
	v_mov_b32_e32 v36, v175
	v_mov_b32_e32 v37, v175
	v_mov_b32_e32 v38, v175
	v_mov_b32_e32 v39, v175
	v_mov_b32_e32 v40, v175
	v_mov_b32_e32 v41, v175
	v_mov_b32_e32 v42, v175
	v_mov_b32_e32 v43, v175
	v_mov_b32_e32 v44, v175
	v_mov_b32_e32 v45, v175
	v_mov_b64_e32 v[78:79], v[46:47]
	v_mov_b64_e32 v[62:63], v[46:47]
	v_mov_b64_e32 v[16:17], v[32:33]
	s_mov_b32 s5, 2
	v_bitop3_b32 v210, v174, v185, v207 bitop3:0xde
	v_bitop3_b32 v211, v192, v185, v207 bitop3:0xde
	v_bitop3_b32 v212, v191, v185, v207 bitop3:0xde
	v_bitop3_b32 v213, v190, v185, v207 bitop3:0xde
	v_bitop3_b32 v214, v189, v185, v207 bitop3:0xde
	v_bitop3_b32 v215, v188, v185, v207 bitop3:0xde
	v_bitop3_b32 v216, v187, v185, v207 bitop3:0xde
	v_bitop3_b32 v217, v186, v185, v207 bitop3:0xde
	v_add_u32_e32 v218, s12, v197
	s_add_i32 s12, s2, 1
	v_lshl_add_u64 v[176:177], s[8:9], 0, v[2:3]
	v_mov_b32_e32 v196, 0
	v_mov_b64_e32 v[76:77], v[44:45]
	v_mov_b64_e32 v[74:75], v[42:43]
	v_mov_b64_e32 v[72:73], v[40:41]
	v_mov_b64_e32 v[70:71], v[38:39]
	v_mov_b64_e32 v[68:69], v[36:37]
	v_mov_b64_e32 v[66:67], v[34:35]
	v_mov_b64_e32 v[64:65], v[32:33]
	v_mov_b64_e32 v[60:61], v[44:45]
	v_mov_b64_e32 v[58:59], v[42:43]
	v_mov_b64_e32 v[56:57], v[40:41]
	v_mov_b64_e32 v[54:55], v[38:39]
	v_mov_b64_e32 v[52:53], v[36:37]
	v_mov_b64_e32 v[50:51], v[34:35]
	v_mov_b64_e32 v[48:49], v[32:33]
	v_mov_b64_e32 v[18:19], v[34:35]
	v_mov_b64_e32 v[20:21], v[36:37]
	v_mov_b64_e32 v[22:23], v[38:39]
	v_mov_b64_e32 v[24:25], v[40:41]
	v_mov_b64_e32 v[26:27], v[42:43]
	v_mov_b64_e32 v[28:29], v[44:45]
	v_mov_b64_e32 v[30:31], v[46:47]
	s_branch .LBB0_223

; #define SWAIT() do { if constexpr (SDEPTH == 1) asm volatile("s_waitcnt vmcnt(0)" ::: "memory"); else if constexpr (MODE == 2) asm volatile("s_waitcnt vmcnt(5)" ::: "memory"); else asm volatile("s_waitcnt vmcnt(4)" ::: "memory"); } while (0)
; #define RESC(a) do { if (__any((a) < 1.f)) { if (hi == 0) al_l[r32] = (a); asm volatile("s_waitcnt lgkmcnt(0)" ::: "memory"); \
;     _Pragma("unroll") for (int d = 0; d < 4; ++d) _Pragma("unroll") for (int r = 0; r < 16; ++r) o[d][r] *= al_l[crow(r, hi)]; } } while (0)
; __device__ __forceinline__ void partialSM(f32x16& p0, f32x16& p1, float& m_reg, float& mn, float& alpha) {
;   float pmax = p0[0];
; #pragma unroll
;   for (int r = 1; r < 16; ++r) pmax = fmaxf(pmax, p0[r]);
; #pragma unroll
;   for (int r = 0; r < 16; ++r) pmax = fmaxf(pmax, p1[r]);
;   { auto rr = __builtin_amdgcn_permlane32_swap(__float_as_uint(pmax), __float_as_uint(pmax), false, false);
;     pmax = fmaxf(__uint_as_float(rr[0]), __uint_as_float(rr[1])); }
;   if (__builtin_expect(__all(pmax - m_reg <= THR), 1)) { mn = m_reg; alpha = 1.f; }
;   else { mn = fmaxf(m_reg, pmax); alpha = __builtin_amdgcn_exp2f(m_reg - mn); m_reg = mn; }
; template <int MODE> ...
;     ...
;     partialSM(pB0, pB1, m_reg, mnB, alB);
;     __syncthreads(); SWAIT(); SWRITE(0, SE);
;     RESC(alB); __syncthreads();
.LBB0_233:
	v_max_f32_e32 v1, v112, v113
	v_max3_f32 v1, v1, v114, v115
	v_max3_f32 v1, v1, v116, v117
	v_max3_f32 v1, v1, v118, v119
	v_max3_f32 v1, v1, v120, v121
	v_max3_f32 v1, v1, v122, v123
	v_max3_f32 v1, v1, v124, v125
	v_max3_f32 v1, v1, v126, v127
	v_max3_f32 v1, v1, v80, v81
	v_max3_f32 v1, v1, v82, v83
	v_max3_f32 v1, v1, v84, v85
	v_max3_f32 v1, v1, v86, v87
	v_max3_f32 v1, v1, v88, v89
	v_max3_f32 v1, v1, v90, v91
	v_max3_f32 v1, v1, v92, v93
	v_max3_f32 v1, v1, v94, v95
	v_mov_b32_e32 v14, v1
	s_nop 1
	v_permlane32_swap_b32_e32 v1, v14
	v_max_f32_e32 v1, v1, v14
	v_sub_f32_e32 v14, v1, v160
	v_cmp_ge_f32_e32 vcc, s58, v14
	v_max_f32_e32 v1, v160, v1
	v_sub_f32_e32 v14, v160, v1
	v_exp_f32_e32 v14, v14
	s_cmp_eq_u64 vcc, exec
	s_cselect_b64 s[40:41], -1, 0
	s_barrier
	s_waitcnt vmcnt(0)
	v_cndmask_b32_e64 v225, v14, 1.0, s[40:41]
	v_cmp_gt_f32_e32 vcc, 1.0, v225
	s_waitcnt vmcnt(3)
	ds_write_b128 v203, v[2:5]
	s_waitcnt vmcnt(1)
	ds_write_b128 v204, v[96:99]
	ds_write_b128 v205, v[6:9] offset:32768
	s_waitcnt vmcnt(0)
	ds_write_b128 v206, v[10:13] offset:32768
	s_cbranch_vccz .LBB0_237
	s_and_saveexec_b64 s[8:9], s[36:37]
	ds_write_b32 v195, v225 offset:128
	s_or_b64 exec, exec, s[8:9]
	s_waitcnt lgkmcnt(0)
	ds_read_b128 v[2:5], v193 offset:224
	ds_read_b128 v[6:9], v193 offset:192
	ds_read_b128 v[10:13], v193 offset:160
	ds_read_b128 v[96:99], v193 offset:128
	s_waitcnt lgkmcnt(3)
	v_pk_mul_f32 v[46:47], v[46:47], v[4:5]
	s_waitcnt lgkmcnt(2)
	v_pk_mul_f32 v[42:43], v[42:43], v[8:9]
	s_waitcnt lgkmcnt(1)
	v_pk_mul_f32 v[38:39], v[38:39], v[12:13]
	s_waitcnt lgkmcnt(0)
	v_pk_mul_f32 v[34:35], v[34:35], v[98:99]
	v_pk_mul_f32 v[44:45], v[44:45], v[2:3]
	v_pk_mul_f32 v[40:41], v[40:41], v[6:7]
	v_pk_mul_f32 v[36:37], v[36:37], v[10:11]
	v_pk_mul_f32 v[32:33], v[32:33], v[96:97]
	v_pk_mul_f32 v[78:79], v[78:79], v[4:5]
	v_pk_mul_f32 v[74:75], v[74:75], v[8:9]
	v_pk_mul_f32 v[70:71], v[70:71], v[12:13]
	v_pk_mul_f32 v[66:67], v[66:67], v[98:99]
	v_pk_mul_f32 v[76:77], v[76:77], v[2:3]
	v_pk_mul_f32 v[72:73], v[72:73], v[6:7]
	v_pk_mul_f32 v[68:69], v[68:69], v[10:11]
	v_pk_mul_f32 v[64:65], v[64:65], v[96:97]
	v_pk_mul_f32 v[62:63], v[62:63], v[4:5]
	v_pk_mul_f32 v[58:59], v[58:59], v[8:9]
	v_pk_mul_f32 v[54:55], v[54:55], v[12:13]
	v_pk_mul_f32 v[50:51], v[50:51], v[98:99]
	v_pk_mul_f32 v[60:61], v[60:61], v[2:3]
	v_pk_mul_f32 v[56:57], v[56:57], v[6:7]
	v_pk_mul_f32 v[52:53], v[52:53], v[10:11]
	v_pk_mul_f32 v[48:49], v[48:49], v[96:97]
	v_pk_mul_f32 v[30:31], v[30:31], v[4:5]
	v_pk_mul_f32 v[26:27], v[26:27], v[8:9]
	v_pk_mul_f32 v[22:23], v[22:23], v[12:13]
	v_pk_mul_f32 v[18:19], v[18:19], v[98:99]
	v_pk_mul_f32 v[28:29], v[28:29], v[2:3]
	v_pk_mul_f32 v[24:25], v[24:25], v[6:7]
	v_pk_mul_f32 v[20:21], v[20:21], v[10:11]
	v_pk_mul_f32 v[16:17], v[16:17], v[96:97]

; #define SWAIT() do { if constexpr (SDEPTH == 1) asm volatile("s_waitcnt vmcnt(0)" ::: "memory"); else if constexpr (MODE == 2) asm volatile("s_waitcnt vmcnt(5)" ::: "memory"); else asm volatile("s_waitcnt vmcnt(4)" ::: "memory"); } while (0)
; #define RESC(a) do { if (__any((a) < 1.f)) { if (hi == 0) al_l[r32] = (a); asm volatile("s_waitcnt lgkmcnt(0)" ::: "memory"); \
;     _Pragma("unroll") for (int d = 0; d < 4; ++d) _Pragma("unroll") for (int r = 0; r < 16; ++r) o[d][r] *= al_l[crow(r, hi)]; } } while (0)
; __device__ __forceinline__ void partialSM(f32x16& p0, f32x16& p1, float& m_reg, float& mn, float& alpha) {
;   float pmax = p0[0];
; #pragma unroll
;   for (int r = 1; r < 16; ++r) pmax = fmaxf(pmax, p0[r]);
; #pragma unroll
;   for (int r = 0; r < 16; ++r) pmax = fmaxf(pmax, p1[r]);
;   { auto rr = __builtin_amdgcn_permlane32_swap(__float_as_uint(pmax), __float_as_uint(pmax), false, false);
;     pmax = fmaxf(__uint_as_float(rr[0]), __uint_as_float(rr[1])); }
;   if (__builtin_expect(__all(pmax - m_reg <= THR), 1)) { mn = m_reg; alpha = 1.f; }
;   else { mn = fmaxf(m_reg, pmax); alpha = __builtin_amdgcn_exp2f(m_reg - mn); m_reg = mn; }
; template <int MODE> ...
;     ...
;     partialSM(pA0, pA1, m_reg, mnA, alA);
;     __syncthreads(); SWAIT(); SWRITE(1, SO);
;     RESC(alA); __syncthreads();
.LBB0_247:
	v_max_f32_e32 v15, v126, v127
	v_max3_f32 v15, v15, v128, v129
	v_max3_f32 v15, v15, v130, v131
	v_max3_f32 v15, v15, v132, v133
	v_max3_f32 v15, v15, v134, v135
	v_max3_f32 v15, v15, v136, v137
	v_max3_f32 v15, v15, v138, v139
	v_max3_f32 v15, v15, v140, v141
	v_max3_f32 v15, v15, v110, v111
	v_max3_f32 v15, v15, v112, v113
	v_max3_f32 v15, v15, v114, v115
	v_max3_f32 v15, v15, v116, v117
	v_max3_f32 v15, v15, v118, v119
	v_max3_f32 v15, v15, v120, v121
	v_max3_f32 v15, v15, v122, v123
	v_max3_f32 v15, v15, v124, v125
	v_mov_b32_e32 v84, v15
	s_nop 1
	v_permlane32_swap_b32_e32 v15, v84
	v_max_f32_e32 v15, v15, v84
	v_sub_f32_e32 v84, v15, v100
	v_cmp_ge_f32_e32 vcc, s58, v84
	v_max_f32_e32 v84, v100, v15
	v_sub_f32_e32 v15, v100, v84
	v_exp_f32_e32 v15, v15
	s_cmp_eq_u64 vcc, exec
	s_cselect_b64 s[38:39], -1, 0
	s_barrier
	s_waitcnt vmcnt(0)
	v_cndmask_b32_e64 v15, v15, 1.0, s[38:39]
	v_cmp_gt_f32_e32 vcc, 1.0, v15
	s_waitcnt vmcnt(3)
	ds_write_b128 v203, v[2:5] offset:16384
	s_waitcnt vmcnt(1)
	ds_write_b128 v204, v[80:83] offset:16384
	ds_write_b128 v205, v[6:9] offset:49152
	s_waitcnt vmcnt(0)
	ds_write_b128 v206, v[10:13] offset:49152
	s_cbranch_vccz .LBB0_222
	s_and_saveexec_b64 s[8:9], s[36:37]
	s_cbranch_execz .LBB0_221
	ds_write_b32 v195, v15 offset:128
	s_branch .LBB0_221

; #define RESC(a) do { if (__any((a) < 1.f)) { if (hi == 0) al_l[r32] = (a); asm volatile("s_waitcnt lgkmcnt(0)" ::: "memory"); \
;     _Pragma("unroll") for (int d = 0; d < 4; ++d) _Pragma("unroll") for (int r = 0; r < 16; ++r) o[d][r] *= al_l[crow(r, hi)]; } } while (0)
; __device__ __forceinline__ void partialSM(f32x16& p0, f32x16& p1, float& m_reg, float& mn, float& alpha) {
;   float pmax = p0[0];
; #pragma unroll
;   for (int r = 1; r < 16; ++r) pmax = fmaxf(pmax, p0[r]);
; #pragma unroll
;   for (int r = 0; r < 16; ++r) pmax = fmaxf(pmax, p1[r]);
;   { auto rr = __builtin_amdgcn_permlane32_swap(__float_as_uint(pmax), __float_as_uint(pmax), false, false);
;     pmax = fmaxf(__uint_as_float(rr[0]), __uint_as_float(rr[1])); }
;   if (__builtin_expect(__all(pmax - m_reg <= THR), 1)) { mn = m_reg; alpha = 1.f; }
;   else { mn = fmaxf(m_reg, pmax); alpha = __builtin_amdgcn_exp2f(m_reg - mn); m_reg = mn; }
; template <int MODE> ...
;     ...
;   partialSM(pB0, pB1, m_reg, mnB, alB);
;   __syncthreads(); RESC(alB);
.LBB0_261:
	v_max_f32_e32 v2, v112, v113
	v_max3_f32 v2, v2, v114, v115
	v_max3_f32 v2, v2, v116, v117
	v_max3_f32 v2, v2, v118, v119
	v_max3_f32 v2, v2, v120, v121
	v_max3_f32 v2, v2, v122, v123
	v_max3_f32 v2, v2, v124, v125
	v_max3_f32 v2, v2, v126, v127
	v_max3_f32 v2, v2, v80, v81
	v_max3_f32 v2, v2, v82, v83
	v_max3_f32 v2, v2, v84, v85
	v_max3_f32 v2, v2, v86, v87
	v_max3_f32 v2, v2, v88, v89
	v_max3_f32 v2, v2, v90, v91
	v_max3_f32 v2, v2, v92, v93
	v_max3_f32 v2, v2, v94, v95
	v_mov_b32_e32 v3, v2
	s_nop 1
	v_permlane32_swap_b32_e32 v2, v3
	v_max_f32_e32 v2, v2, v3
	v_sub_f32_e32 v3, v2, v160
	v_cmp_ge_f32_e32 vcc, s58, v3
	v_max_f32_e32 v2, v160, v2
	v_sub_f32_e32 v3, v160, v2
	v_exp_f32_e32 v3, v3
	s_cmp_eq_u64 vcc, exec
	s_cselect_b64 s[38:39], -1, 0
	v_cndmask_b32_e64 v15, v3, 1.0, s[38:39]
	v_cmp_gt_f32_e32 vcc, 1.0, v15
	s_barrier
	s_cbranch_vccz .LBB0_265
	v_cmp_gt_u32_e32 vcc, 32, v184
	s_and_saveexec_b64 s[8:9], vcc
	ds_write_b32 v195, v15 offset:128
	s_or_b64 exec, exec, s[8:9]
	s_waitcnt lgkmcnt(0)
	ds_read_b128 v[4:7], v193 offset:224
	ds_read_b128 v[8:11], v193 offset:192
	ds_read_b128 v[96:99], v193 offset:160
	ds_read_b128 v[100:103], v193 offset:128
	s_waitcnt lgkmcnt(3)
	v_pk_mul_f32 v[46:47], v[46:47], v[6:7]
	s_waitcnt lgkmcnt(2)
	v_pk_mul_f32 v[42:43], v[42:43], v[10:11]
	s_waitcnt lgkmcnt(1)
	v_pk_mul_f32 v[38:39], v[38:39], v[98:99]
	s_waitcnt lgkmcnt(0)
	v_pk_mul_f32 v[34:35], v[34:35], v[102:103]
	v_pk_mul_f32 v[44:45], v[44:45], v[4:5]
	v_pk_mul_f32 v[40:41], v[40:41], v[8:9]
	v_pk_mul_f32 v[36:37], v[36:37], v[96:97]
	v_pk_mul_f32 v[32:33], v[32:33], v[100:101]
	v_pk_mul_f32 v[78:79], v[78:79], v[6:7]
	v_pk_mul_f32 v[74:75], v[74:75], v[10:11]
	v_pk_mul_f32 v[70:71], v[70:71], v[98:99]
	v_pk_mul_f32 v[66:67], v[66:67], v[102:103]
	v_pk_mul_f32 v[76:77], v[76:77], v[4:5]
	v_pk_mul_f32 v[72:73], v[72:73], v[8:9]
	v_pk_mul_f32 v[68:69], v[68:69], v[96:97]
	v_pk_mul_f32 v[64:65], v[64:65], v[100:101]
	v_pk_mul_f32 v[62:63], v[62:63], v[6:7]
	v_pk_mul_f32 v[58:59], v[58:59], v[10:11]
	v_pk_mul_f32 v[54:55], v[54:55], v[98:99]
	v_pk_mul_f32 v[50:51], v[50:51], v[102:103]
	v_pk_mul_f32 v[60:61], v[60:61], v[4:5]
	v_pk_mul_f32 v[56:57], v[56:57], v[8:9]
	v_pk_mul_f32 v[52:53], v[52:53], v[96:97]
	v_pk_mul_f32 v[48:49], v[48:49], v[100:101]
	v_pk_mul_f32 v[30:31], v[30:31], v[6:7]
	v_pk_mul_f32 v[26:27], v[26:27], v[10:11]
	v_pk_mul_f32 v[22:23], v[22:23], v[98:99]
	v_pk_mul_f32 v[18:19], v[18:19], v[102:103]
	v_pk_mul_f32 v[28:29], v[28:29], v[4:5]
	v_pk_mul_f32 v[24:25], v[24:25], v[8:9]
	v_pk_mul_f32 v[20:21], v[20:21], v[96:97]
	v_pk_mul_f32 v[16:17], v[16:17], v[100:101]

; template <int MODE> ...
;     ...
;   const bf16_t* Qw = Qb + (long)(wid * QBLK + r32) * ldq + hi * 8;
;   if constexpr (MODE == 1) {
; #pragma unroll
;     for (int d0 = 0; d0 < 8; ++d0) *reinterpret_cast<bf16x8*>(Q2s + KSWZ(r32, (d0 * 16 + hi * 8) * 2)) = *reinterpret_cast<const bf16x8*>(Qw + d0 * 16);
;     asm volatile("s_waitcnt lgkmcnt(0)" ::: "memory");
;   } else if constexpr (MODE == 2) {
; #pragma unroll
;     for (int d0 = 0; d0 < 3; ++d0) qr[d0] = *reinterpret_cast<const bf16x8*>(Qw + d0 * 16);
;     *reinterpret_cast<bf16x8*>(Q3s) = *reinterpret_cast<const bf16x8*>(Qw + 3 * 16);
; #pragma unroll
;     for (int d0 = 4; d0 < 8; ++d0) *reinterpret_cast<bf16x8*>(QHs + K2SWZ(r32, ((d0 - 4) * 16 + hi * 8) * 2)) = *reinterpret_cast<const bf16x8*>(Qw + d0 * 16);
;     asm volatile("s_waitcnt lgkmcnt(0)" ::: "memory");
;   } else {
; #pragma unroll
;     for (int d0 = 0; d0 < 8; ++d0) qr[d0] = *reinterpret_cast<const bf16x8*>(Qw + d0 * 16);
;   }
;   if constexpr (MODE == 2) { const bf16_t* Q2w = Q2b + (long)(wid * QBLK + r32) * ldq2 + hi * 8;
; #pragma unroll
;     for (int d0 = 0; d0 < 4; ++d0) *reinterpret_cast<bf16x8*>(Q2s + K2SWZ(r32, (d0 * 16 + hi * 8) * 2)) = *reinterpret_cast<const bf16x8*>(Q2w + d0 * 16);
;     asm volatile("s_waitcnt lgkmcnt(0)" ::: "memory"); }
;     ...
;             const int half = ui >> 8, it = ui & 255, xcd = it & 7, slot = it >> 3, bh = xcd * 4 + (slot >> 3), p = slot & 7, qb = half ? p : 15 - p, b = bh >> 3, h = bh & 7;
;             const size_t qrow = (size_t)b * SEQ + 256 * qb, krow = (size_t)b * SEQ;
;     ...
;             att::attn_unit<2>(lds, QB + qrow * QW + h * 128, QB + qrow * QW + 1024 + h * 64, KVB + krow * KVW + h * 128, KVB + krow * KVW + 1024 + h * 128, KR + krow * 64,
;                               OB + qrow * DM + 1024 + h * 128, QW, QW, KVW, DM, 4 * qb + 4, 4 * qb, 0, nullptr);
.LBB0_270:
	s_and_b64 vcc, exec, s[4:5]
	s_cbranch_vccz .LBB0_206
	s_lshl_b32 s2, s35, 7
	s_and_b32 s24, s2, 0x180000
	s_lshl_b32 s2, s35, 12
	s_and_b32 s38, s2, 0x3000000
	s_and_b32 s2, s14, 1
	s_bfe_u32 s3, s54, 0x20006
	s_lshl_b32 s4, s3, 8
	s_lshl_b32 s2, s2, 10
	s_or_b32 s59, s2, s4
	s_bfe_u32 s4, s54, 0x30003
	s_lshl_b32 s2, s54, 2
	s_xor_b32 s5, s4, 15
	s_cmpk_lt_u32 s54, 0x100
	s_cselect_b32 s8, s5, s4
	s_and_b32 s2, s2, 4
	s_or_b32 s4, s2, s3
	s_lshl_b32 s2, s54, 11
	s_and_b32 s5, s2, 0x3000
	s_lshl_b32 s2, s8, 8
	s_or_b32 s3, s2, s5
	s_mul_i32 s2, s3, 0xc00
	v_readlane_b32 s6, v251, 54
	v_readlane_b32 s7, v251, 55
	s_add_u32 s6, s6, s2
	s_addc_u32 s7, s7, 0
	s_lshl_b32 s2, s4, 7
	s_lshl_b32 s4, s4, 8
	s_add_u32 s10, s6, s4
	s_addc_u32 s11, s7, 0
	s_add_u32 s6, s6, s2
	s_addc_u32 s7, s7, 0
	s_lshl_b32 s9, s5, 12
	v_readlane_b32 s12, v251, 56
	v_readlane_b32 s13, v251, 57
	s_add_u32 s9, s12, s9
	s_addc_u32 s12, s13, 0
	s_add_u32 s36, s9, s4
	s_addc_u32 s37, s12, 0
	s_add_u32 s52, s36, 0x800
	s_addc_u32 s53, s37, 0
	s_lshl_b32 s4, s5, 7
	v_readlane_b32 s12, v250, 0
	v_mov_b32_e32 v58, v198
	v_readlane_b32 s13, v250, 1
	s_add_u32 s4, s12, s4
	s_addc_u32 s5, s13, 0
	v_readfirstlane_b32 s9, v58
	s_ashr_i32 s12, s9, 6
	v_and_b32_e32 v1, 31, v58
	s_lshl_b32 s40, s12, 5
	v_bfe_u32 v118, v58, 5, 1
	v_or_b32_e32 v5, s40, v1
	v_mov_b64_e32 v[2:3], s[10:11]
	s_movk_i32 s13, 0xc00
	v_mad_i64_i32 v[2:3], s[10:11], v5, s13, v[2:3]
	v_lshlrev_b32_e32 v174, 4, v118
	v_lshl_add_u64 v[2:3], v[2:3], 0, v[174:175]
	global_load_dwordx4 v[6:9], v[2:3], off offset:96
	global_load_dwordx4 v[10:13], v[2:3], off offset:128
	global_load_dwordx4 v[14:17], v[2:3], off offset:160
	global_load_dwordx4 v[18:21], v[2:3], off offset:192
	global_load_dwordx4 v[22:25], v[2:3], off offset:224
	v_mov_b64_e32 v[26:27], s[6:7]
	s_lshl_b32 s6, s12, 12
	v_lshlrev_b32_e32 v34, 3, v58
	s_movk_i32 s10, 0x70
	s_lshl_b32 s7, s12, 10
	s_add_i32 s12, s6, 0
	v_and_b32_e32 v59, 63, v58
	v_lshlrev_b32_e32 v70, 7, v1
	v_and_b32_e32 v4, 0x70, v34
	v_bitop3_b32 v35, v174, v34, s10 bitop3:0x78
	s_movk_i32 s10, 0x60
	s_add_i32 s7, s7, 0
	s_add_i32 s6, s12, 0x1d000
	v_lshlrev_b32_e32 v61, 4, v59
	v_bitop3_b32 v36, v174, v4, 32 bitop3:0x36
	v_bitop3_b32 v37, v174, v4, 64 bitop3:0x36
	v_bitop3_b32 v38, v174, v4, s10 bitop3:0x36
	s_add_i32 s7, s7, 0x25000
	v_mad_i64_i32 v[26:27], s[10:11], v5, s13, v[26:27]
	v_add_u32_e32 v5, s6, v70
	v_add_u32_e32 v122, s7, v61
	global_load_dwordx4 v[106:109], v[2:3], off
	global_load_dwordx4 v[102:105], v[2:3], off offset:32
	global_load_dwordx4 v[98:101], v[2:3], off offset:64
	v_add_u32_e32 v2, v5, v35
	v_add_u32_e32 v3, v5, v36
	v_add_u32_e32 v28, v5, v37
	v_add_u32_e32 v5, v5, v38
	v_lshl_add_u64 v[26:27], v[26:27], 0, v[174:175]
	s_add_i32 s65, s12, 0x15000
	s_mov_b64 s[10:11], 0x20000
	v_lshlrev_b32_e32 v71, 8, v1
	s_ashr_i32 s23, s9, 7
	v_or_b32_e32 v72, 32, v1
	v_lshlrev_b32_e32 v74, 8, v72
	v_or_b32_e32 v73, 32, v174
	v_bitop3_b32 v144, v174, v70, v4 bitop3:0xde
	v_add_u32_e32 v138, s6, v144
	v_bitop3_b32 v150, v73, v70, v4 bitop3:0xde
	v_add_u32_e32 v141, s6, v150
	v_add_u32_e32 v149, s65, v144
	v_add_u32_e32 v152, s65, v150
	s_mov_b32 s7, s25
	s_mov_b32 s12, s25
	s_mov_b32 s13, s25
	s_mov_b32 s14, s25
	s_mov_b32 s15, s25
	s_mov_b32 s16, s25
	s_mov_b32 s17, s25
	s_mov_b32 s18, s25
	v_lshlrev_b32_e32 v78, 1, v58
	v_lshlrev_b32_e32 v79, 3, v59
	v_and_b32_e32 v61, 0xc0, v61
	v_and_b32_e32 v78, 32, v78
	v_and_b32_e32 v80, 0x100, v79
	v_and_or_b32 v61, v79, 24, v61
	v_or3_b32 v61, v61, v78, v80
	s_mov_b32 s39, s25
	s_mov_b32 s55, 2
	v_mov_b32_e32 v120, 0
	s_waitcnt vmcnt(0)
	ds_write_b128 v122, v[6:9]
	s_waitcnt vmcnt(6)
	ds_write_b128 v2, v[10:13]
	s_waitcnt vmcnt(5)
	ds_write_b128 v3, v[14:17]
	s_waitcnt vmcnt(4)
	ds_write_b128 v28, v[18:21]
	s_waitcnt vmcnt(3)
	ds_write_b128 v5, v[22:25]
	s_waitcnt lgkmcnt(0)
	global_load_dwordx4 v[6:9], v[26:27], off offset:2048
	global_load_dwordx4 v[10:13], v[26:27], off offset:2080
	global_load_dwordx4 v[14:17], v[26:27], off offset:2112
	global_load_dwordx4 v[18:21], v[26:27], off offset:2144
	v_ashrrev_i32_e32 v28, 3, v58
	v_ashrrev_i32_e32 v29, 31, v28
	v_ashrrev_i32_e32 v26, 4, v58
	v_lshlrev_b32_e32 v2, 4, v58
	v_and_b32_e32 v244, 0xf0, v2
	v_lshlrev_b64 v[52:53], 7, v[28:29]
	v_mov_b32_e32 v3, v175
	v_and_b32_e32 v5, 0x78, v34
	v_ashrrev_i32_e32 v27, 31, v26
	v_and_b32_e32 v2, 0x70, v2
	v_lshl_add_u64 v[32:33], s[4:5], 0, v[52:53]
	v_lshlrev_b32_e32 v5, 1, v5
	v_lshlrev_b64 v[50:51], 12, v[26:27]
	v_lshl_add_u64 v[54:55], v[32:33], 0, v[2:3]
	v_add_u32_e32 v3, s65, v70
	v_or_b32_e32 v56, v50, v5
	v_mov_b32_e32 v57, v51
	v_add_u32_e32 v27, v3, v35
	v_add_u32_e32 v29, v3, v36
	v_add_u32_e32 v32, v3, v37
	v_add_u32_e32 v3, v3, v38
	v_lshl_add_u64 v[22:23], v[56:57], 0, s[10:11]
	v_lshl_add_u64 v[24:25], s[36:37], 0, v[56:57]
	v_lshl_add_u64 v[30:31], s[36:37], 0, v[22:23]
	v_lshl_add_u64 v[22:23], s[52:53], 0, v[22:23]
	v_add_u32_e32 v33, 32, v26
	v_lshlrev_b32_e32 v28, 7, v28
	s_and_b32 s5, s9, 0x3fffffc0
	s_lshl_b32 s5, s5, 2
	s_lshl_b32 s4, s8, 2
	s_add_i32 s22, s5, 0
	s_add_i32 s33, s4, 4
	s_add_i32 s41, s23, s4
	s_add_i32 s22, s22, 0x10000
	s_cmp_lg_u32 0, -1
	s_cselect_b32 s61, 0, 0
	s_add_i32 s19, 0, 0x11000
	v_add_u32_e32 v155, s19, v144
	v_add_u32_e32 v158, s19, v150
	s_cmp_gt_i32 s41, -1
	s_cselect_b64 vcc, -1, 0
	s_mov_b32 s4, s25
	s_mov_b32 s5, s25
	s_mov_b32 s8, s25
	s_mov_b32 s9, s25
	s_mov_b32 s10, s25
	s_mov_b32 s11, s25
	v_lshl_add_u64 v[110:111], s[24:25], 0, v[52:53]
	v_add_u32_e32 v137, s61, v61
	v_lshl_add_u64 v[112:113], s[38:39], 0, v[50:51]
	v_lshl_add_u32 v119, v1, 2, s22
	s_waitcnt vmcnt(3)
; #define KFRAG(d, hf) (((d) < 8) ? *reinterpret_cast<const bf16x8*>(Ks + KSWZ((hf) * 32 + r32, ((d) * 16 + hi * 8) * 2)) \
;                                 : *reinterpret_cast<const bf16x8*>(K2s + K2SWZ((hf) * 32 + r32, (((d) - 8) * 16 + hi * 8) * 2)))
; #define QLDS(d) (((d) == 3) ? *reinterpret_cast<const bf16x8*>(Q3s) : ((d) < 8) ? *reinterpret_cast<const bf16x8*>(QHs + K2SWZ(r32, (((d) - 4) * 16 + hi * 8) * 2)) \
;                            : *reinterpret_cast<const bf16x8*>(Q2s + K2SWZ(r32, (((d) - 8) * 16 + hi * 8) * 2)))
; template <int MODE>
; __device__ __forceinline__ void qkt(f32x16& p0, f32x16& p1, const char* Ks, const char* K2s, const bf16x8* qr, const char* Q2s, const char* QHs, const char* Q3s, int r32, int hi, bool valid) {
;     ...
;     p0 = f32x16{}; p1 = f32x16{};
;     constexpr int ND = (MODE == 2) ? 12 : 8;
;     bf16x8 ka[2], kb[2];
;     ka[0] = KFRAG(0, 0); kb[0] = KFRAG(0, 1);
; #pragma unroll
;     for (int d = 0; d < ND; ++d) {
;       bf16x8 q; if (MODE == 2 && d >= 3) q = QLDS(d); else q = qr[d < 8 ? d : 0];
;       if (d + 1 < ND) { ka[(d + 1) & 1] = KFRAG(d + 1, 0); kb[(d + 1) & 1] = KFRAG(d + 1, 1); }
;       p0 = __builtin_amdgcn_mfma_f32_32x32x16_bf16(ka[d & 1], q, p0, 0, 0, 0);
;       p1 = __builtin_amdgcn_mfma_f32_32x32x16_bf16(kb[d & 1], q, p1, 0, 0, 0);
;     }
; template <int MODE> ...
;     ...
;   if constexpr (MODE == 2) { const bf16_t* Q2w = Q2b + (long)(wid * QBLK + r32) * ldq2 + hi * 8;
; #pragma unroll
;     for (int d0 = 0; d0 < 4; ++d0) *reinterpret_cast<bf16x8*>(Q2s + K2SWZ(r32, (d0 * 16 + hi * 8) * 2)) = *reinterpret_cast<const bf16x8*>(Q2w + d0 * 16);
;     asm volatile("s_waitcnt lgkmcnt(0)" ::: "memory"); }
;   const int sr = tid >> 4, sc = (tid & 15) * 8, vst0 = v_st(sr, sc), vst1 = v_st(32 + sr, sc);
;   const int s2r = tid >> 3, s2c = (tid & 7) * 8;
;   const int vb0 = (int)(uintptr_t)V_lds + v_rd_base(lane);
;   const int relq = (qc0 - kc0) * 64 + wid * 32 + r32 - 4 * hi;
;   struct { bf16x8 vs0, vs1, ks0, ks1, k2; } sr_[SDEPTH];
;     ...
;   f32x16 pA0, pA1, pB0, pB1; float mnA, mnB, alA, alB; bf16x8 pa0, pa1, pa2, pa3;
;   constexpr int SE = 0, SO = SDEPTH - 1;
;   SLOAD(SE, 0); asm volatile("s_waitcnt vmcnt(0)" ::: "memory"); SWRITE(0, SE); __syncthreads();
;   QKT(pA0, pA1, 0, 0); partialSM(pA0, pA1, m_reg, mnA, alA);
	ds_write_b128 v27, v[6:9]
	s_waitcnt vmcnt(2)
	ds_write_b128 v29, v[10:13]
	s_waitcnt vmcnt(1)
	ds_write_b128 v32, v[14:17]
	s_waitcnt vmcnt(0)
	ds_write_b128 v3, v[18:21]
	s_waitcnt lgkmcnt(0)
	global_load_dwordx4 v[6:9], v[24:25], off offset:2048
	global_load_dwordx4 v[10:13], v[22:23], off
	global_load_dwordx4 v[14:17], v[24:25], off
	global_load_dwordx4 v[18:21], v[30:31], off
	v_and_b32_e32 v27, 0xfffff0, v26
	global_load_dwordx4 v[22:25], v[54:55], off
	v_lshlrev_b32_e32 v29, 1, v26
	v_lshrrev_b32_e32 v30, 1, v26
	v_and_b32_e32 v32, 3, v26
	v_and_b32_e32 v3, 0x70, v58
	v_and_b32_e32 v245, 0xf0, v58
	v_and_or_b32 v27, v29, 8, v27
	v_and_or_b32 v29, v30, 4, v32
	v_and_b32_e32 v30, 0xfffff0, v33
	v_lshlrev_b32_e32 v32, 1, v33
	v_lshlrev_b32_e32 v26, 8, v26
	v_bitop3_b32 v60, v2, v28, v3 bitop3:0xde
	v_bitop3_b32 v28, v174, v71, v244 bitop3:0xde
	v_and_or_b32 v30, v32, 8, v30
	v_bfe_u32 v31, v34, 5, 2
	v_lshlrev_b32_e32 v33, 8, v33
	v_lshrrev_b32_e32 v27, 1, v27
	v_bitop3_b32 v26, v5, v26, v245 bitop3:0xde
	v_add_u32_e32 v123, 0, v28
	v_lshrrev_b32_e32 v28, 1, v30
	v_bitop3_b32 v3, v5, v33, v245 bitop3:0xde
	v_or_b32_e32 v27, v27, v31
	v_add_u32_e32 v124, 0, v26
	v_or_b32_e32 v26, v28, v31
	v_lshlrev_b32_e32 v29, 6, v29
	v_and_b32_e32 v34, 48, v5
	v_add_u32_e32 v125, 0, v3
	v_lshlrev_b32_e32 v3, 9, v27
	v_lshlrev_b32_e32 v26, 9, v26
	v_or3_b32 v3, v3, v29, v34
	v_or3_b32 v26, v26, v29, v34
	v_add_u32_e32 v126, 0, v3
	v_add_u32_e32 v127, 0, v26
	v_add_u32_e32 v3, s19, v60
	s_waitcnt vmcnt(0)
	v_bitop3_b32 v5, v174, v74, v244 bitop3:0xde
	v_add_u32_e32 v128, 0, v5
	v_add_u32_e32 v169, 0, v60
	v_add_u32_e32 v170, 0x13000, v169
	s_waitcnt vmcnt(4)
	ds_write_b128 v126, v[6:9]
	s_waitcnt vmcnt(3)
	ds_write_b128 v127, v[10:13]
	s_waitcnt vmcnt(2)
	ds_write_b128 v124, v[14:17] offset:32768
	s_waitcnt vmcnt(1)
	ds_write_b128 v125, v[18:21] offset:32768
	v_bitop3_b32 v10, v73, v74, v244 bitop3:0xde
	s_waitcnt vmcnt(0)
	ds_write_b128 v3, v[22:25]
	s_waitcnt lgkmcnt(0)
	s_barrier
	ds_read_b128 v[6:9], v123 offset:32768
	v_add_u32_e32 v130, 0, v10
	ds_read_b128 v[10:13], v128 offset:32768
	v_bitop3_b32 v3, v73, v71, v244 bitop3:0xde
	v_add_u32_e32 v129, 0, v3
	ds_read_b128 v[14:17], v129 offset:32768
	ds_read_b128 v[62:65], v130 offset:32768
	s_waitcnt lgkmcnt(3)
	v_mfma_f32_32x32x16_bf16 v[18:33], v[6:9], v[106:109], 0
	v_or_b32_e32 v3, 64, v174
	v_bitop3_b32 v5, v3, v71, v244 bitop3:0xde
	v_bitop3_b32 v6, v3, v74, v244 bitop3:0xde
	v_add_u32_e32 v131, 0, v5
	v_add_u32_e32 v132, 0, v6
	v_or_b32_e32 v5, 0x60, v174
	v_bitop3_b32 v151, v3, v70, v4 bitop3:0xde
	s_waitcnt lgkmcnt(2)
	v_mfma_f32_32x32x16_bf16 v[34:49], v[10:13], v[106:109], 0
	ds_read_b128 v[6:9], v131 offset:32768
	ds_read_b128 v[10:13], v132 offset:32768
	v_add_u32_e32 v145, s6, v151
	v_bitop3_b32 v153, v5, v70, v4 bitop3:0xde
	v_add_u32_e32 v148, s6, v153
	v_add_u32_e32 v163, s19, v151
	v_add_u32_e32 v160, s65, v151
	s_waitcnt lgkmcnt(3)
	v_mfma_f32_32x32x16_bf16 v[18:33], v[14:17], v[102:105], v[18:33]
	v_bitop3_b32 v14, v5, v71, v244 bitop3:0xde
	v_bitop3_b32 v15, v5, v74, v244 bitop3:0xde
	v_add_u32_e32 v133, 0, v14
	v_add_u32_e32 v134, 0, v15
	v_add_u32_e32 v166, s19, v153
	v_add_u32_e32 v161, s65, v153
	s_mov_b32 s6, s25
	s_waitcnt lgkmcnt(2)
	v_mfma_f32_32x32x16_bf16 v[34:49], v[62:65], v[102:105], v[34:49]
	ds_read_b128 v[14:17], v133 offset:32768
	ds_read_b128 v[62:65], v134 offset:32768
	s_movk_i32 s65, 0x2000
	s_waitcnt lgkmcnt(3)
	v_mfma_f32_32x32x16_bf16 v[18:33], v[6:9], v[98:101], v[18:33]
	v_or_b32_e32 v6, 0x80, v174
	s_waitcnt lgkmcnt(2)
	v_mfma_f32_32x32x16_bf16 v[34:49], v[10:13], v[98:101], v[34:49]
	v_bitop3_b32 v10, v6, v71, v244 bitop3:0xde
	v_bitop3_b32 v11, v6, v74, v244 bitop3:0xde
	ds_read_b128 v[6:9], v122
	v_add_u32_e32 v135, 0, v10
	v_add_u32_e32 v136, 0, v11
	ds_read_b128 v[10:13], v135 offset:32768
	ds_read_b128 v[66:69], v136 offset:32768
	s_waitcnt lgkmcnt(2)
	v_mfma_f32_32x32x16_bf16 v[18:33], v[14:17], v[6:9], v[18:33]
	v_or_b32_e32 v14, 0xa0, v174
	v_bitop3_b32 v15, v14, v71, v244 bitop3:0xde
	v_bitop3_b32 v14, v14, v74, v244 bitop3:0xde
	v_add_u32_e32 v139, 0, v15
	v_add_u32_e32 v140, 0, v14
	v_mfma_f32_32x32x16_bf16 v[34:49], v[62:65], v[6:9], v[34:49]
	ds_read_b128 v[6:9], v138
	ds_read_b128 v[14:17], v139 offset:32768
	ds_read_b128 v[62:65], v140 offset:32768
	s_waitcnt lgkmcnt(2)
	v_mfma_f32_32x32x16_bf16 v[18:33], v[10:13], v[6:9], v[18:33]
	v_or_b32_e32 v10, 0xc0, v174
	v_bitop3_b32 v11, v10, v71, v244 bitop3:0xde
	v_bitop3_b32 v10, v10, v74, v244 bitop3:0xde
	v_add_u32_e32 v142, 0, v11
	v_add_u32_e32 v143, 0, v10
	v_mfma_f32_32x32x16_bf16 v[34:49], v[66:69], v[6:9], v[34:49]
	ds_read_b128 v[6:9], v141
	ds_read_b128 v[10:13], v142 offset:32768
	ds_read_b128 v[66:69], v143 offset:32768
	s_waitcnt lgkmcnt(2)
	v_mfma_f32_32x32x16_bf16 v[18:33], v[14:17], v[6:9], v[18:33]
	v_or_b32_e32 v14, 0xe0, v174
	v_bitop3_b32 v15, v14, v71, v244 bitop3:0xde
	v_bitop3_b32 v2, v14, v74, v244 bitop3:0xde
	v_add_u32_e32 v146, 0, v15
	v_add_u32_e32 v147, 0, v2
	v_lshlrev_b32_e32 v2, 7, v72
	v_bitop3_b32 v154, v174, v2, v4 bitop3:0xde
	v_mfma_f32_32x32x16_bf16 v[34:49], v[62:65], v[6:9], v[34:49]
	ds_read_b128 v[6:9], v145
	ds_read_b128 v[14:17], v146 offset:32768
	ds_read_b128 v[62:65], v147 offset:32768
	v_add_u32_e32 v156, s19, v154
	v_bitop3_b32 v157, v73, v2, v4 bitop3:0xde
	v_add_u32_e32 v159, s19, v157
	v_bitop3_b32 v162, v3, v2, v4 bitop3:0xde
	s_waitcnt lgkmcnt(2)
	v_mfma_f32_32x32x16_bf16 v[18:33], v[10:13], v[6:9], v[18:33]
	v_add_u32_e32 v164, s19, v162
	v_bitop3_b32 v165, v5, v2, v4 bitop3:0xde
	v_add_u32_e32 v167, s19, v165
	s_mov_b32 s19, s25
	v_mfma_f32_32x32x16_bf16 v[34:49], v[66:69], v[6:9], v[34:49]
	ds_read_b128 v[6:9], v148
	ds_read_b128 v[10:13], v155
	ds_read_b128 v[66:69], v156
	s_waitcnt lgkmcnt(2)
; __device__ __forceinline__ void partialSM(f32x16& p0, f32x16& p1, float& m_reg, float& mn, float& alpha) {
;   float pmax = p0[0];
; #pragma unroll
;   for (int r = 1; r < 16; ++r) pmax = fmaxf(pmax, p0[r]);
; #pragma unroll
;   for (int r = 0; r < 16; ++r) pmax = fmaxf(pmax, p1[r]);
;   { auto rr = __builtin_amdgcn_permlane32_swap(__float_as_uint(pmax), __float_as_uint(pmax), false, false);
;     pmax = fmaxf(__uint_as_float(rr[0]), __uint_as_float(rr[1])); }
;   if (__builtin_expect(__all(pmax - m_reg <= THR), 1)) { mn = m_reg; alpha = 1.f; }
;   else { mn = fmaxf(m_reg, pmax); alpha = __builtin_amdgcn_exp2f(m_reg - mn); m_reg = mn; }
; #pragma unroll
;   for (int r = 0; r < 16; ++r) p0[r] = p0[r] - mn;
; #pragma unroll
;   for (int r = 0; r < 16; ++r) p1[r] = p1[r] - mn;
; #pragma unroll
;   for (int r = 0; r < 16; ++r) p0[r] = __builtin_amdgcn_exp2f(p0[r]);
; }
; template <int MODE>
; __device__ __forceinline__ void qkt(f32x16& p0, f32x16& p1, const char* Ks, const char* K2s, const bf16x8* qr, const char* Q2s, const char* QHs, const char* Q3s, int r32, int hi, bool valid) {
;     ...
;     p0 = f32x16{}; p1 = f32x16{};
;     constexpr int ND = (MODE == 2) ? 12 : 8;
;     bf16x8 ka[2], kb[2];
;     ka[0] = KFRAG(0, 0); kb[0] = KFRAG(0, 1);
; #pragma unroll
;     for (int d = 0; d < ND; ++d) {
;       bf16x8 q; if (MODE == 2 && d >= 3) q = QLDS(d); else q = qr[d < 8 ? d : 0];
;       if (d + 1 < ND) { ka[(d + 1) & 1] = KFRAG(d + 1, 0); kb[(d + 1) & 1] = KFRAG(d + 1, 1); }
;       p0 = __builtin_amdgcn_mfma_f32_32x32x16_bf16(ka[d & 1], q, p0, 0, 0, 0);
;       p1 = __builtin_amdgcn_mfma_f32_32x32x16_bf16(kb[d & 1], q, p1, 0, 0, 0);
;     }
;     __builtin_amdgcn_sched_group_barrier(0x100, 2, 0);
; #pragma unroll
;     for (int d = 0; d < ND; ++d) {
;       { const int nrd = ((MODE == 2 && d >= 3) ? 1 : 0) + ((d + 1 < ND) ? 2 : 0);
;         if (nrd == 3) __builtin_amdgcn_sched_group_barrier(0x100, 3, 0); else if (nrd == 2) __builtin_amdgcn_sched_group_barrier(0x100, 2, 0); else if (nrd == 1) __builtin_amdgcn_sched_group_barrier(0x100, 1, 0); }
;       __builtin_amdgcn_sched_group_barrier(0x008, 2, 0);
;     }
;     if constexpr (MODE == 2) {
;       const float msk = valid ? 0.f : -INFINITY;
; #pragma unroll
;       for (int r = 0; r < 16; ++r) { p0[r] = valid ? p0[r] : msk; p1[r] = valid ? p1[r] : msk; }
;     }
	v_mfma_f32_32x32x16_bf16 v[18:33], v[14:17], v[6:9], v[18:33]
	v_mfma_f32_32x32x16_bf16 v[34:49], v[62:65], v[6:9], v[34:49]
	ds_read_b128 v[6:9], v149
	ds_read_b128 v[14:17], v158
	ds_read_b128 v[62:65], v159
	s_waitcnt lgkmcnt(2)
	v_mfma_f32_32x32x16_bf16 v[18:33], v[10:13], v[6:9], v[18:33]
	v_mfma_f32_32x32x16_bf16 v[34:49], v[66:69], v[6:9], v[34:49]
	ds_read_b128 v[6:9], v152
	ds_read_b128 v[10:13], v163
	ds_read_b128 v[66:69], v164
	s_waitcnt lgkmcnt(2)
	v_mfma_f32_32x32x16_bf16 v[18:33], v[14:17], v[6:9], v[18:33]
	v_mfma_f32_32x32x16_bf16 v[34:49], v[62:65], v[6:9], v[34:49]
	ds_read_b128 v[62:65], v160
	ds_read_b128 v[70:73], v166
	ds_read_b128 v[74:77], v167
	s_waitcnt lgkmcnt(2)
	v_mfma_f32_32x32x16_bf16 v[18:33], v[10:13], v[62:65], v[18:33]
	v_mov_b64_e32 v[2:3], s[4:5]
	v_mov_b64_e32 v[4:5], s[6:7]
	v_mov_b64_e32 v[6:7], s[8:9]
	v_mov_b64_e32 v[8:9], s[10:11]
	v_mov_b64_e32 v[10:11], s[12:13]
	v_mov_b64_e32 v[12:13], s[14:15]
	v_mov_b64_e32 v[14:15], s[16:17]
	v_mfma_f32_32x32x16_bf16 v[34:49], v[66:69], v[62:65], v[34:49]
	ds_read_b128 v[62:65], v161
	v_mov_b64_e32 v[16:17], s[18:19]
	s_mov_b64 s[4:5], 0x40000
	v_lshl_add_u64 v[66:67], v[56:57], 0, s[4:5]
	s_mov_b64 s[4:5], 0x60000
	v_lshl_add_u64 v[56:57], v[56:57], 0, s[4:5]
	v_lshl_add_u64 v[78:79], s[36:37], 0, v[66:67]
	s_waitcnt lgkmcnt(0)
	v_mfma_f32_32x32x16_bf16 v[18:33], v[70:73], v[62:65], v[18:33]
	v_lshl_add_u64 v[66:67], s[52:53], 0, v[66:67]
	v_lshl_add_u64 v[70:71], s[52:53], 0, v[56:57]
	global_load_dwordx4 v[66:69], v[66:67], off
	s_nop 0
	global_load_dwordx4 v[70:73], v[70:71], off
	s_nop 6
	v_cndmask_b32_e32 v80, v0, v26, vcc
	v_mfma_f32_32x32x16_bf16 v[34:49], v[74:77], v[62:65], v[34:49]
	v_cndmask_b32_e32 v62, v0, v18, vcc
	v_cndmask_b32_e32 v63, v0, v19, vcc
	v_max_f32_e32 v18, v63, v63
	v_max_f32_e32 v19, v62, v62
	v_cndmask_b32_e32 v64, v0, v20, vcc
	v_cndmask_b32_e32 v65, v0, v21, vcc
	v_max_f32_e32 v18, v19, v18
	v_cndmask_b32_e32 v74, v0, v22, vcc
	v_cndmask_b32_e32 v75, v0, v23, vcc
	v_max3_f32 v18, v18, v64, v65
	v_cndmask_b32_e32 v76, v0, v24, vcc
	v_cndmask_b32_e32 v77, v0, v25, vcc
	v_max3_f32 v18, v18, v74, v75
	v_cndmask_b32_e32 v81, v0, v27, vcc
	v_max3_f32 v18, v18, v76, v77
	v_cndmask_b32_e32 v82, v0, v28, vcc
	v_cndmask_b32_e32 v83, v0, v29, vcc
	v_max3_f32 v18, v18, v80, v81
	v_cndmask_b32_e32 v30, v0, v30, vcc
	v_cndmask_b32_e32 v31, v0, v31, vcc
	v_max3_f32 v18, v18, v82, v83
	v_max3_f32 v84, v18, v30, v31
	global_load_dwordx4 v[18:21], v[78:79], off
	v_cndmask_b32_e32 v34, v0, v34, vcc
	v_cndmask_b32_e32 v35, v0, v35, vcc
	v_cndmask_b32_e32 v36, v0, v36, vcc
	v_cndmask_b32_e32 v37, v0, v37, vcc
	v_cndmask_b32_e32 v38, v0, v38, vcc
	v_cndmask_b32_e32 v39, v0, v39, vcc
	v_cndmask_b32_e32 v40, v0, v40, vcc
	v_cndmask_b32_e32 v41, v0, v41, vcc
	v_cndmask_b32_e32 v42, v0, v42, vcc
	v_cndmask_b32_e32 v43, v0, v43, vcc
	v_cndmask_b32_e32 v44, v0, v44, vcc
	v_cndmask_b32_e32 v45, v0, v45, vcc
	v_cndmask_b32_e32 v46, v0, v46, vcc
	v_cndmask_b32_e32 v47, v0, v47, vcc
	v_cndmask_b32_e32 v32, v0, v32, vcc
	v_cndmask_b32_e32 v48, v0, v48, vcc
	v_cndmask_b32_e32 v33, v0, v33, vcc
	v_cndmask_b32_e32 v49, v0, v49, vcc
	v_add_co_u32_e32 v26, vcc, s65, v54
	v_lshl_add_u64 v[22:23], s[36:37], 0, v[56:57]
	s_nop 0
	v_addc_co_u32_e32 v27, vcc, 0, v55, vcc
	global_load_dwordx4 v[22:25], v[22:23], off
	v_max3_f32 v54, v84, v32, v33
	global_load_dwordx4 v[26:29], v[26:27], off
	v_max3_f32 v54, v54, v34, v35
	v_max3_f32 v54, v54, v36, v37
	v_max3_f32 v54, v54, v38, v39
	v_max3_f32 v54, v54, v40, v41
	v_max3_f32 v54, v54, v42, v43
	v_max3_f32 v54, v54, v44, v45
	v_max3_f32 v54, v54, v46, v47
	v_max3_f32 v54, v54, v48, v49
	v_mov_b32_e32 v55, v54
	s_nop 1
	v_permlane32_swap_b32_e32 v54, v55
	v_max_f32_e32 v54, v54, v55
	v_add_f32_e32 v55, 0x7149f2ca, v54
	v_max_f32_e32 v54, 0xf149f2ca, v54
	v_cmp_ge_f32_e32 vcc, s58, v55
	v_sub_f32_e32 v55, 0xf149f2ca, v54
	v_exp_f32_e32 v55, v55
	s_cmp_eq_u64 vcc, exec
	s_cselect_b64 vcc, -1, 0
	v_cndmask_b32_e32 v171, v54, v202, vcc
	v_cndmask_b32_e64 v168, v55, 1.0, vcc
	v_sub_f32_e32 v54, v62, v171
	v_sub_f32_e32 v55, v63, v171
	v_sub_f32_e32 v56, v64, v171
	v_sub_f32_e32 v57, v65, v171
	v_sub_f32_e32 v62, v74, v171
	v_sub_f32_e32 v63, v75, v171
	v_sub_f32_e32 v64, v76, v171
	v_sub_f32_e32 v65, v77, v171
	v_sub_f32_e32 v74, v80, v171
	v_sub_f32_e32 v75, v81, v171
	v_sub_f32_e32 v76, v82, v171
	v_sub_f32_e32 v77, v83, v171
	v_sub_f32_e32 v30, v30, v171
	v_sub_f32_e32 v31, v31, v171
	v_sub_f32_e32 v32, v32, v171
	v_sub_f32_e32 v33, v33, v171
	s_waitcnt vmcnt(0)
	s_waitcnt vmcnt(4)
	ds_write_b128 v126, v[66:69] offset:16384
	s_waitcnt vmcnt(3)
	ds_write_b128 v127, v[70:73] offset:16384
	v_exp_f32_e32 v220, v54
	v_exp_f32_e32 v221, v55
	v_exp_f32_e32 v222, v56
	v_exp_f32_e32 v223, v57
	v_exp_f32_e32 v224, v62
	v_exp_f32_e32 v225, v63
	v_exp_f32_e32 v226, v64
	v_exp_f32_e32 v227, v65
	v_exp_f32_e32 v115, v74
	v_exp_f32_e32 v116, v75
	v_exp_f32_e32 v117, v76
	s_waitcnt vmcnt(2)
	ds_write_b128 v124, v[18:21] offset:49152
	v_and_b32_e32 v18, 7, v58
	v_exp_f32_e32 v214, v77
	v_exp_f32_e32 v216, v30
	v_exp_f32_e32 v217, v31
	v_exp_f32_e32 v218, v32
	v_exp_f32_e32 v219, v33
	v_lshl_or_b32 v110, v18, 4, v110
	v_and_b32_e32 v18, 15, v58
	s_addk_i32 s61, 0x4000
	v_lshlrev_b32_e32 v18, 4, v18
	v_sub_f32_e32 v228, v34, v171
	v_sub_f32_e32 v229, v35, v171
	v_sub_f32_e32 v230, v36, v171
	v_sub_f32_e32 v231, v37, v171
	v_sub_f32_e32 v232, v38, v171
	v_sub_f32_e32 v233, v39, v171
	v_sub_f32_e32 v234, v40, v171
	v_sub_f32_e32 v235, v41, v171
	v_sub_f32_e32 v236, v42, v171
	v_sub_f32_e32 v237, v43, v171
	v_sub_f32_e32 v238, v44, v171
	v_sub_f32_e32 v239, v45, v171
	v_sub_f32_e32 v240, v46, v171
	v_sub_f32_e32 v242, v47, v171
	v_sub_f32_e32 v243, v48, v171
	v_sub_f32_e32 v241, v49, v171
	s_waitcnt vmcnt(1)
	ds_write_b128 v125, v[22:25] offset:49152
	s_waitcnt vmcnt(0)
	ds_write_b128 v170, v[26:29]
	v_cmp_gt_u32_e64 s[36:37], 32, v59
	v_add_u32_e32 v121, s61, v61
	v_or3_b32 v112, v112, v18, s59
	v_mov_b64_e32 v[64:65], v[16:17]
	v_mov_b64_e32 v[48:49], v[16:17]
	v_mov_b64_e32 v[32:33], v[16:17]
	s_movk_i32 s59, 0x6000
	v_mov_b64_e32 v[62:63], v[14:15]
	v_mov_b64_e32 v[60:61], v[12:13]
	v_mov_b64_e32 v[58:59], v[10:11]
	v_mov_b64_e32 v[56:57], v[8:9]
	v_mov_b64_e32 v[54:55], v[6:7]
	v_mov_b64_e32 v[52:53], v[4:5]
	v_mov_b64_e32 v[50:51], v[2:3]
	v_mov_b64_e32 v[46:47], v[14:15]
	v_mov_b64_e32 v[44:45], v[12:13]
	v_mov_b64_e32 v[42:43], v[10:11]
	v_mov_b64_e32 v[40:41], v[8:9]
	v_mov_b64_e32 v[38:39], v[6:7]
	v_mov_b64_e32 v[36:37], v[4:5]
	v_mov_b64_e32 v[34:35], v[2:3]
	v_mov_b64_e32 v[30:31], v[14:15]
	v_mov_b64_e32 v[28:29], v[12:13]
	v_mov_b64_e32 v[26:27], v[10:11]
	v_mov_b64_e32 v[24:25], v[8:9]
	v_mov_b64_e32 v[22:23], v[6:7]
	v_mov_b64_e32 v[20:21], v[4:5]
	v_mov_b64_e32 v[18:19], v[2:3]
	s_waitcnt lgkmcnt(0)
	s_barrier
; #define KFRAG(d, hf) (((d) < 8) ? *reinterpret_cast<const bf16x8*>(Ks + KSWZ((hf) * 32 + r32, ((d) * 16 + hi * 8) * 2)) \
;                                 : *reinterpret_cast<const bf16x8*>(K2s + K2SWZ((hf) * 32 + r32, (((d) - 8) * 16 + hi * 8) * 2)))
; __device__ __forceinline__ void finishSM(f32x16& p0, f32x16& p1, float alpha, float& l_reg, bf16x8& pa0, bf16x8& pa1, bf16x8& pa2, bf16x8& pa3) {
; #pragma unroll
;   for (int r = 0; r < 16; ++r) p1[r] = __builtin_amdgcn_exp2f(p1[r]);
;   float ps = 0;
; #pragma unroll
;   for (int r = 0; r < 16; ++r) ps += p0[r];
; #pragma unroll
;   for (int r = 0; r < 16; ++r) ps += p1[r];
;   { auto rr = __builtin_amdgcn_permlane32_swap(__float_as_uint(ps), __float_as_uint(ps), false, false);
;     ps = __uint_as_float(rr[0]) + __uint_as_float(rr[1]); }
;   l_reg = l_reg * alpha + ps;
;     ...
;   PK4(p0, 0, pa0); PK4(p0, 8, pa1); PK4(p1, 0, pa2); PK4(p1, 8, pa3);
; template <int MODE>
; __device__ __forceinline__ void qkt(f32x16& p0, f32x16& p1, const char* Ks, const char* K2s, const bf16x8* qr, const char* Q2s, const char* QHs, const char* Q3s, int r32, int hi, bool valid) {
;     ...
;     p0 = f32x16{}; p1 = f32x16{};
;     constexpr int ND = (MODE == 2) ? 12 : 8;
;     bf16x8 ka[2], kb[2];
;     ka[0] = KFRAG(0, 0); kb[0] = KFRAG(0, 1);
; #pragma unroll
;     for (int d = 0; d < ND; ++d) {
;       bf16x8 q; if (MODE == 2 && d >= 3) q = QLDS(d); else q = qr[d < 8 ? d : 0];
;       if (d + 1 < ND) { ka[(d + 1) & 1] = KFRAG(d + 1, 0); kb[(d + 1) & 1] = KFRAG(d + 1, 1); }
;       p0 = __builtin_amdgcn_mfma_f32_32x32x16_bf16(ka[d & 1], q, p0, 0, 0, 0);
;       p1 = __builtin_amdgcn_mfma_f32_32x32x16_bf16(kb[d & 1], q, p1, 0, 0, 0);
;     }
;     __builtin_amdgcn_sched_group_barrier(0x100, 2, 0);
; #pragma unroll
;     for (int d = 0; d < ND; ++d) {
;       { const int nrd = ((MODE == 2 && d >= 3) ? 1 : 0) + ((d + 1 < ND) ? 2 : 0);
;         if (nrd == 3) __builtin_amdgcn_sched_group_barrier(0x100, 3, 0); else if (nrd == 2) __builtin_amdgcn_sched_group_barrier(0x100, 2, 0); else if (nrd == 1) __builtin_amdgcn_sched_group_barrier(0x100, 1, 0); }
;       __builtin_amdgcn_sched_group_barrier(0x008, 2, 0);
;     }
;     if constexpr (MODE == 2) {
;       const float msk = valid ? 0.f : -INFINITY;
; #pragma unroll
;       for (int r = 0; r < 16; ++r) { p0[r] = valid ? p0[r] : msk; p1[r] = valid ? p1[r] : msk; }
;     }
.LBB0_272:
	s_add_i32 s6, s55, -1
	ds_read_b128 v[82:85], v128 offset:49152
	ds_read_b128 v[66:69], v123 offset:49152
	ds_read_b128 v[186:189], v130 offset:49152
	ds_read_b128 v[182:185], v129 offset:49152
	s_cmp_gt_i32 s6, s41
	s_cselect_b64 vcc, -1, 0
	s_add_i32 s4, 0, 0x13000
	v_add_u32_e32 v173, s4, v154
	v_add_u32_e32 v172, s4, v144
	s_waitcnt lgkmcnt(3)
	v_mfma_f32_32x32x16_bf16 v[82:97], v[82:85], v[106:109], 0
	v_add_u32_e32 v177, s4, v157
	v_add_u32_e32 v176, s4, v150
	s_waitcnt lgkmcnt(2)
	v_mfma_f32_32x32x16_bf16 v[66:81], v[66:69], v[106:109], 0
	ds_read_b128 v[194:197], v132 offset:49152
	ds_read_b128 v[190:193], v131 offset:49152
	s_waitcnt lgkmcnt(3)
	v_mfma_f32_32x32x16_bf16 v[82:97], v[186:189], v[102:105], v[82:97]
	s_waitcnt lgkmcnt(2)
	v_mfma_f32_32x32x16_bf16 v[66:81], v[182:185], v[102:105], v[66:81]
	ds_read_b128 v[186:189], v134 offset:49152
	ds_read_b128 v[182:185], v133 offset:49152
	s_waitcnt lgkmcnt(3)
	v_mfma_f32_32x32x16_bf16 v[82:97], v[194:197], v[98:101], v[82:97]
	s_waitcnt lgkmcnt(2)
	v_mfma_f32_32x32x16_bf16 v[66:81], v[190:193], v[98:101], v[66:81]
	ds_read_b128 v[190:193], v122
	ds_read_b128 v[204:207], v136 offset:49152
	ds_read_b128 v[194:197], v135 offset:49152
	s_waitcnt lgkmcnt(2)
	v_mfma_f32_32x32x16_bf16 v[82:97], v[186:189], v[190:193], v[82:97]
	v_mfma_f32_32x32x16_bf16 v[66:81], v[182:185], v[190:193], v[66:81]
	ds_read_b128 v[182:185], v138
	ds_read_b128 v[190:193], v140 offset:49152
	ds_read_b128 v[186:189], v139 offset:49152
	s_waitcnt lgkmcnt(2)
	v_mfma_f32_32x32x16_bf16 v[82:97], v[204:207], v[182:185], v[82:97]
	v_mfma_f32_32x32x16_bf16 v[66:81], v[194:197], v[182:185], v[66:81]
	ds_read_b128 v[182:185], v141
	ds_read_b128 v[204:207], v143 offset:49152
	ds_read_b128 v[194:197], v142 offset:49152
	s_waitcnt lgkmcnt(2)
	v_mfma_f32_32x32x16_bf16 v[82:97], v[190:193], v[182:185], v[82:97]
	v_mfma_f32_32x32x16_bf16 v[66:81], v[186:189], v[182:185], v[66:81]
	ds_read_b128 v[182:185], v145
	ds_read_b128 v[190:193], v147 offset:49152
	ds_read_b128 v[186:189], v146 offset:49152
	s_waitcnt lgkmcnt(2)
	v_mfma_f32_32x32x16_bf16 v[82:97], v[204:207], v[182:185], v[82:97]
	v_mfma_f32_32x32x16_bf16 v[66:81], v[194:197], v[182:185], v[66:81]
	ds_read_b128 v[182:185], v148
	ds_read_b128 v[204:207], v173
	ds_read_b128 v[194:197], v172
	s_waitcnt lgkmcnt(2)
	v_mfma_f32_32x32x16_bf16 v[82:97], v[190:193], v[182:185], v[82:97]
	v_mfma_f32_32x32x16_bf16 v[66:81], v[186:189], v[182:185], v[66:81]
	ds_read_b128 v[182:185], v149
	ds_read_b128 v[190:193], v177
	ds_read_b128 v[186:189], v176
	s_waitcnt lgkmcnt(2)
	v_mfma_f32_32x32x16_bf16 v[82:97], v[204:207], v[182:185], v[82:97]
	v_mfma_f32_32x32x16_bf16 v[66:81], v[194:197], v[182:185], v[66:81]
	ds_read_b128 v[194:197], v152
	v_add_u32_e32 v183, s4, v162
	v_add_u32_e32 v182, s4, v151
	ds_read_b128 v[208:211], v183
	ds_read_b128 v[204:207], v182
	v_add_u32_e32 v185, s4, v165
	v_add_u32_e32 v184, s4, v153
	s_waitcnt lgkmcnt(2)
	v_mfma_f32_32x32x16_bf16 v[82:97], v[190:193], v[194:197], v[82:97]
	v_mfma_f32_32x32x16_bf16 v[66:81], v[186:189], v[194:197], v[66:81]
	ds_read_b128 v[186:189], v160
	ds_read_b128 v[194:197], v185
	ds_read_b128 v[190:193], v184
	s_waitcnt lgkmcnt(2)
	v_mfma_f32_32x32x16_bf16 v[82:97], v[208:211], v[186:189], v[82:97]
	v_mfma_f32_32x32x16_bf16 v[66:81], v[204:207], v[186:189], v[66:81]
	ds_read_b128 v[186:189], v161
	s_waitcnt lgkmcnt(0)
	v_mfma_f32_32x32x16_bf16 v[82:97], v[194:197], v[186:189], v[82:97]
	v_mfma_f32_32x32x16_bf16 v[66:81], v[190:193], v[186:189], v[66:81]
	s_nop 10
	v_cndmask_b32_e32 v189, v82, v0, vcc
	v_add_f32_e32 v82, 0, v220
	v_add_f32_e32 v82, v221, v82
	v_add_f32_e32 v82, v222, v82
	v_add_f32_e32 v82, v223, v82
	v_add_f32_e32 v82, v224, v82
	v_add_f32_e32 v82, v225, v82
	v_add_f32_e32 v82, v226, v82
	v_add_f32_e32 v82, v227, v82
	v_add_f32_e32 v82, v115, v82
	v_add_f32_e32 v82, v116, v82
	v_add_f32_e32 v82, v117, v82
	v_add_f32_e32 v82, v214, v82
	v_cndmask_b32_e32 v193, v66, v0, vcc
	v_exp_f32_e32 v66, v228
	v_add_f32_e32 v82, v216, v82
	v_cndmask_b32_e32 v194, v67, v0, vcc
	v_exp_f32_e32 v67, v229
	v_add_f32_e32 v82, v217, v82
	v_cndmask_b32_e32 v195, v68, v0, vcc
	v_exp_f32_e32 v68, v230
	v_add_f32_e32 v82, v218, v82
	v_cndmask_b32_e32 v196, v69, v0, vcc
	v_exp_f32_e32 v69, v231
	v_add_f32_e32 v82, v219, v82
	v_cndmask_b32_e32 v197, v70, v0, vcc
	v_exp_f32_e32 v70, v232
	v_add_f32_e32 v82, v66, v82
	v_cndmask_b32_e32 v203, v71, v0, vcc
	v_exp_f32_e32 v71, v233
	v_add_f32_e32 v82, v67, v82
	v_cndmask_b32_e32 v204, v72, v0, vcc
	v_exp_f32_e32 v72, v234
	v_add_f32_e32 v82, v68, v82
	v_cndmask_b32_e32 v205, v73, v0, vcc
	v_exp_f32_e32 v73, v235
	v_add_f32_e32 v82, v69, v82
	v_cndmask_b32_e32 v206, v74, v0, vcc
	v_exp_f32_e32 v74, v236
	v_add_f32_e32 v82, v70, v82
	v_cndmask_b32_e32 v207, v75, v0, vcc
	v_exp_f32_e32 v75, v237
	v_add_f32_e32 v82, v71, v82
	v_cndmask_b32_e32 v208, v76, v0, vcc
	v_exp_f32_e32 v76, v238
	v_add_f32_e32 v82, v72, v82
	v_cndmask_b32_e32 v209, v77, v0, vcc
	v_exp_f32_e32 v77, v239
	v_add_f32_e32 v82, v73, v82
	v_cndmask_b32_e32 v210, v78, v0, vcc
	v_exp_f32_e32 v78, v240
	v_add_f32_e32 v82, v74, v82
	v_cndmask_b32_e32 v211, v79, v0, vcc
	v_exp_f32_e32 v79, v242
	v_add_f32_e32 v82, v75, v82
	v_cndmask_b32_e32 v212, v80, v0, vcc
	v_exp_f32_e32 v80, v243
	v_add_f32_e32 v82, v76, v82
	v_cndmask_b32_e32 v213, v81, v0, vcc
	v_exp_f32_e32 v81, v241
	v_add_f32_e32 v82, v77, v82
	v_add_f32_e32 v82, v78, v82
	v_add_f32_e32 v82, v79, v82
	v_add_f32_e32 v82, v80, v82
	v_add_f32_e32 v186, v81, v82
	v_mov_b32_e32 v187, v186
	v_cvt_pk_bf16_f32 v220, v220, v221
	v_cvt_pk_bf16_f32 v221, v222, v223
; #define SBAR() __builtin_amdgcn_sched_barrier(0)
; __device__ __forceinline__ void partialSM(f32x16& p0, f32x16& p1, float& m_reg, float& mn, float& alpha) {
;   float pmax = p0[0];
; #pragma unroll
;   for (int r = 1; r < 16; ++r) pmax = fmaxf(pmax, p0[r]);
; #pragma unroll
;   for (int r = 0; r < 16; ++r) pmax = fmaxf(pmax, p1[r]);
;   { auto rr = __builtin_amdgcn_permlane32_swap(__float_as_uint(pmax), __float_as_uint(pmax), false, false);
;     pmax = fmaxf(__uint_as_float(rr[0]), __uint_as_float(rr[1])); }
;   if (__builtin_expect(__all(pmax - m_reg <= THR), 1)) { mn = m_reg; alpha = 1.f; }
;   else { mn = fmaxf(m_reg, pmax); alpha = __builtin_amdgcn_exp2f(m_reg - mn); m_reg = mn; }
; template <int D0> __device__ __forceinline__ void pv_one(f32x16& od, int vb, bf16x8 pa0, bf16x8 pa1, bf16x8 pa2, bf16x8 pa3) {
;   const s16x4 l0 = tr_read<v_rd_off(D0, 0, 0)>(vb), h0 = tr_read<v_rd_off(D0, 0, 1)>(vb), l1 = tr_read<v_rd_off(D0, 1, 0)>(vb), h1 = tr_read<v_rd_off(D0, 1, 1)>(vb);
;   const s16x4 l2 = tr_read<v_rd_off(D0, 2, 0)>(vb), h2 = tr_read<v_rd_off(D0, 2, 1)>(vb), l3 = tr_read<v_rd_off(D0, 3, 0)>(vb), h3 = tr_read<v_rd_off(D0, 3, 1)>(vb);
;   asm volatile("s_waitcnt lgkmcnt(0)" ::: "memory"); SBAR();
;     ...
;   od = __builtin_amdgcn_mfma_f32_32x32x16_bf16(pa0, PK(l0, h0), od, 0, 0, 0);
;   od = __builtin_amdgcn_mfma_f32_32x32x16_bf16(pa1, PK(l1, h1), od, 0, 0, 0);
;   od = __builtin_amdgcn_mfma_f32_32x32x16_bf16(pa2, PK(l2, h2), od, 0, 0, 0);
;   od = __builtin_amdgcn_mfma_f32_32x32x16_bf16(pa3, PK(l3, h3), od, 0, 0, 0);
;     ...
; }
; __device__ __forceinline__ void pv_d0(f32x16* o, int vb, bf16x8 pa0, bf16x8 pa1, bf16x8 pa2, bf16x8 pa3) {
;   pv_one<0>(o[0], vb, pa0, pa1, pa2, pa3); pv_one<1>(o[1], vb, pa0, pa1, pa2, pa3); pv_one<2>(o[2], vb, pa0, pa1, pa2, pa3); pv_one<3>(o[3], vb, pa0, pa1, pa2, pa3);
	v_cvt_pk_bf16_f32 v222, v224, v225
	v_cvt_pk_bf16_f32 v223, v226, v227
	v_cvt_pk_bf16_f32 v225, v117, v214
	v_cvt_pk_bf16_f32 v226, v216, v217
	v_cvt_pk_bf16_f32 v214, v66, v67
	v_cvt_pk_bf16_f32 v216, v70, v71
	v_cndmask_b32_e32 v190, v83, v0, vcc
	v_cndmask_b32_e32 v191, v84, v0, vcc
	v_cndmask_b32_e32 v192, v85, v0, vcc
	v_cndmask_b32_e32 v86, v86, v0, vcc
	v_cndmask_b32_e32 v87, v87, v0, vcc
	v_cndmask_b32_e32 v88, v88, v0, vcc
	v_cndmask_b32_e32 v89, v89, v0, vcc
	v_cndmask_b32_e32 v90, v90, v0, vcc
	v_cndmask_b32_e32 v91, v91, v0, vcc
	v_cndmask_b32_e32 v92, v92, v0, vcc
	v_cndmask_b32_e32 v93, v93, v0, vcc
	v_cndmask_b32_e32 v94, v94, v0, vcc
	v_cndmask_b32_e32 v95, v95, v0, vcc
	v_cndmask_b32_e32 v96, v96, v0, vcc
	v_cndmask_b32_e32 v97, v97, v0, vcc
	v_permlane32_swap_b32_e32 v186, v187
	v_cvt_pk_bf16_f32 v224, v115, v116
	v_cvt_pk_bf16_f32 v227, v218, v219
	v_cvt_pk_bf16_f32 v215, v68, v69
	v_cvt_pk_bf16_f32 v217, v72, v73
	v_permlane32_swap_b32_e32 v214, v216
	v_cvt_pk_bf16_f32 v228, v74, v75
	v_cvt_pk_bf16_f32 v229, v76, v77
	v_cvt_pk_bf16_f32 v230, v78, v79
	v_cvt_pk_bf16_f32 v231, v80, v81
	v_permlane32_swap_b32_e32 v220, v222
	v_permlane32_swap_b32_e32 v221, v223
	v_permlane32_swap_b32_e32 v224, v226
	v_permlane32_swap_b32_e32 v225, v227
	v_permlane32_swap_b32_e32 v215, v217
	v_permlane32_swap_b32_e32 v228, v230
	v_permlane32_swap_b32_e32 v229, v231
	v_lshl_add_u64 v[114:115], s[88:89], 0, v[112:113]
	s_mov_b32 s4, 0x2b880000
	v_add_co_u32_e32 v70, vcc, s4, v114
	s_mov_b32 s4, 0x2b8a0000
	s_nop 0
	v_addc_co_u32_e32 v71, vcc, 0, v115, vcc
	v_add_co_u32_e32 v74, vcc, s4, v114
	v_lshl_add_u64 v[116:117], s[88:89], 0, v[110:111]
	s_nop 0
	v_addc_co_u32_e32 v75, vcc, 0, v115, vcc
	s_mov_b32 s4, 0x1204000
	v_add_co_u32_e32 v82, vcc, s4, v116
	global_load_dwordx4 v[66:69], v[70:71], off offset:2048
	s_nop 0
	v_addc_co_u32_e32 v83, vcc, 0, v117, vcc
	global_load_dwordx4 v[70:73], v[70:71], off
	s_nop 0
	global_load_dwordx4 v[78:81], v[74:75], off offset:2048
	s_nop 0
	global_load_dwordx4 v[74:77], v[74:75], off
	s_nop 0
	global_load_dwordx4 v[82:85], v[82:83], off
	ds_read_b64_tr_b16 v[232:233], v137 offset:0
	ds_read_b64_tr_b16 v[234:235], v137 offset:0x800
	ds_read_b64_tr_b16 v[236:237], v137 offset:0x1000
	ds_read_b64_tr_b16 v[238:239], v137 offset:0x1800
	ds_read_b64_tr_b16 v[240:241], v137 offset:0x2000
	ds_read_b64_tr_b16 v[242:243], v137 offset:0x2800
	ds_read_b64_tr_b16 v[244:245], v137 offset:0x3000
	ds_read_b64_tr_b16 v[246:247], v137 offset:0x3800
	s_waitcnt lgkmcnt(0)
	s_nop 0
	v_mfma_f32_32x32x16_bf16 v[2:17], v[220:223], v[232:235], v[2:17]
	ds_read_b64_tr_b16 v[232:233], v137 offset:0x200
	ds_read_b64_tr_b16 v[234:235], v137 offset:0xa00
	v_mfma_f32_32x32x16_bf16 v[2:17], v[224:227], v[236:239], v[2:17]
	ds_read_b64_tr_b16 v[236:237], v137 offset:0x1200
	ds_read_b64_tr_b16 v[238:239], v137 offset:0x1a00
	v_mfma_f32_32x32x16_bf16 v[2:17], v[214:217], v[240:243], v[2:17]
	ds_read_b64_tr_b16 v[240:241], v137 offset:0x2200
	ds_read_b64_tr_b16 v[242:243], v137 offset:0x2a00
	v_mfma_f32_32x32x16_bf16 v[2:17], v[228:231], v[244:247], v[2:17]
	ds_read_b64_tr_b16 v[244:245], v137 offset:0x3200
	ds_read_b64_tr_b16 v[246:247], v137 offset:0x3a00
	s_waitcnt lgkmcnt(0)
	v_mfma_f32_32x32x16_bf16 v[50:65], v[220:223], v[232:235], v[50:65]
	ds_read_b64_tr_b16 v[232:233], v137 offset:0x400
	ds_read_b64_tr_b16 v[234:235], v137 offset:0xc00
	v_mfma_f32_32x32x16_bf16 v[50:65], v[224:227], v[236:239], v[50:65]
	ds_read_b64_tr_b16 v[236:237], v137 offset:0x1400
	ds_read_b64_tr_b16 v[238:239], v137 offset:0x1c00
	v_mfma_f32_32x32x16_bf16 v[50:65], v[214:217], v[240:243], v[50:65]
	ds_read_b64_tr_b16 v[240:241], v137 offset:0x2400
	ds_read_b64_tr_b16 v[242:243], v137 offset:0x2c00
	v_mfma_f32_32x32x16_bf16 v[50:65], v[228:231], v[244:247], v[50:65]
	ds_read_b64_tr_b16 v[244:245], v137 offset:0x3400
	ds_read_b64_tr_b16 v[246:247], v137 offset:0x3c00
	s_waitcnt lgkmcnt(0)
	v_mfma_f32_32x32x16_bf16 v[34:49], v[220:223], v[232:235], v[34:49]
	ds_read_b64_tr_b16 v[232:233], v137 offset:0x600
	ds_read_b64_tr_b16 v[234:235], v137 offset:0xe00
	v_mfma_f32_32x32x16_bf16 v[34:49], v[224:227], v[236:239], v[34:49]
	ds_read_b64_tr_b16 v[236:237], v137 offset:0x1600
	ds_read_b64_tr_b16 v[238:239], v137 offset:0x1e00
	v_mfma_f32_32x32x16_bf16 v[34:49], v[214:217], v[240:243], v[34:49]
	ds_read_b64_tr_b16 v[240:241], v137 offset:0x2600
	ds_read_b64_tr_b16 v[242:243], v137 offset:0x2e00
	v_mfma_f32_32x32x16_bf16 v[34:49], v[228:231], v[244:247], v[34:49]
	ds_read_b64_tr_b16 v[244:245], v137 offset:0x3600
	ds_read_b64_tr_b16 v[246:247], v137 offset:0x3e00
	s_waitcnt lgkmcnt(0)
	v_mfma_f32_32x32x16_bf16 v[18:33], v[220:223], v[232:235], v[18:33]
	v_max_f32_e32 v188, v194, v194
	s_barrier
	s_waitcnt vmcnt(0)
	s_waitcnt vmcnt(4)
	ds_write_b128 v126, v[66:69]
	v_add_u32_e32 v66, 0x11000, v169
	v_mfma_f32_32x32x16_bf16 v[18:33], v[224:227], v[236:239], v[18:33]
	s_waitcnt vmcnt(2)
	ds_write_b128 v127, v[78:81]
	ds_write_b128 v124, v[70:73] offset:32768
	s_waitcnt vmcnt(1)
	ds_write_b128 v125, v[74:77] offset:32768
	s_waitcnt vmcnt(0)
	ds_write_b128 v66, v[82:85]
	v_mfma_f32_32x32x16_bf16 v[18:33], v[214:217], v[240:243], v[18:33]
	v_max_f32_e32 v188, v193, v188
	v_max3_f32 v188, v188, v195, v196
	v_max3_f32 v188, v188, v197, v203
	v_max3_f32 v188, v188, v204, v205
	v_max3_f32 v188, v188, v206, v207
	v_max3_f32 v188, v188, v208, v209
	v_max3_f32 v188, v188, v210, v211
	v_max3_f32 v188, v188, v212, v213
	v_max3_f32 v188, v188, v189, v190
	v_max3_f32 v188, v188, v191, v192
	v_max3_f32 v188, v188, v86, v87
	v_max3_f32 v188, v188, v88, v89
	v_max3_f32 v188, v188, v90, v91
	v_max3_f32 v188, v188, v92, v93
	v_max3_f32 v188, v188, v94, v95
	v_max3_f32 v188, v188, v96, v97
	v_mov_b32_e32 v214, v188
	s_nop 1
	v_permlane32_swap_b32_e32 v188, v214
	v_max_f32_e32 v188, v188, v214
	v_sub_f32_e32 v214, v188, v171
	v_cmp_ge_f32_e32 vcc, s58, v214
	v_mfma_f32_32x32x16_bf16 v[18:33], v[228:231], v[244:247], v[18:33]
	v_max_f32_e32 v214, v171, v188
	v_sub_f32_e32 v188, v171, v214
	v_exp_f32_e32 v188, v188
	s_cmp_eq_u64 vcc, exec
	s_cselect_b64 s[38:39], -1, 0
	v_cndmask_b32_e64 v188, v188, 1.0, s[38:39]
	v_cmp_gt_f32_e32 vcc, 1.0, v188
	s_cbranch_vccz .LBB0_276
; #define KFRAG(d, hf) (((d) < 8) ? *reinterpret_cast<const bf16x8*>(Ks + KSWZ((hf) * 32 + r32, ((d) * 16 + hi * 8) * 2)) \
;                                 : *reinterpret_cast<const bf16x8*>(K2s + K2SWZ((hf) * 32 + r32, (((d) - 8) * 16 + hi * 8) * 2)))
; #define QLDS(d) (((d) == 3) ? *reinterpret_cast<const bf16x8*>(Q3s) : ((d) < 8) ? *reinterpret_cast<const bf16x8*>(QHs + K2SWZ(r32, (((d) - 4) * 16 + hi * 8) * 2)) \
;                            : *reinterpret_cast<const bf16x8*>(Q2s + K2SWZ(r32, (((d) - 8) * 16 + hi * 8) * 2)))
; template <int MODE>
; __device__ __forceinline__ void qkt(f32x16& p0, f32x16& p1, const char* Ks, const char* K2s, const bf16x8* qr, const char* Q2s, const char* QHs, const char* Q3s, int r32, int hi, bool valid) {
;     ...
;     p0 = f32x16{}; p1 = f32x16{};
;     constexpr int ND = (MODE == 2) ? 12 : 8;
;     bf16x8 ka[2], kb[2];
;     ka[0] = KFRAG(0, 0); kb[0] = KFRAG(0, 1);
; #pragma unroll
;     for (int d = 0; d < ND; ++d) {
;       bf16x8 q; if (MODE == 2 && d >= 3) q = QLDS(d); else q = qr[d < 8 ? d : 0];
;       if (d + 1 < ND) { ka[(d + 1) & 1] = KFRAG(d + 1, 0); kb[(d + 1) & 1] = KFRAG(d + 1, 1); }
;       p0 = __builtin_amdgcn_mfma_f32_32x32x16_bf16(ka[d & 1], q, p0, 0, 0, 0);
;       p1 = __builtin_amdgcn_mfma_f32_32x32x16_bf16(kb[d & 1], q, p1, 0, 0, 0);
;     }
	s_and_saveexec_b64 s[4:5], s[36:37]
	ds_write_b32 v119, v188 offset:128
	s_or_b64 exec, exec, s[4:5]
	s_waitcnt lgkmcnt(0)
	v_add_u32_e32 v78, s22, v174
	ds_read_b128 v[66:69], v78 offset:224
	ds_read_b128 v[70:73], v78 offset:192
	ds_read_b128 v[74:77], v78 offset:160
	ds_read_b128 v[78:81], v78 offset:128
	s_waitcnt lgkmcnt(3)
	v_pk_mul_f32 v[14:15], v[14:15], v[66:67]
	s_waitcnt lgkmcnt(2)
	v_pk_mul_f32 v[10:11], v[10:11], v[70:71]
	s_waitcnt lgkmcnt(1)
	v_pk_mul_f32 v[6:7], v[6:7], v[74:75]
	v_pk_mul_f32 v[16:17], v[16:17], v[68:69]
	v_pk_mul_f32 v[12:13], v[12:13], v[72:73]
	v_pk_mul_f32 v[8:9], v[8:9], v[76:77]
	s_waitcnt lgkmcnt(0)
	v_pk_mul_f32 v[4:5], v[4:5], v[80:81]
	v_pk_mul_f32 v[2:3], v[2:3], v[78:79]
	v_pk_mul_f32 v[62:63], v[62:63], v[66:67]
	v_pk_mul_f32 v[58:59], v[58:59], v[70:71]
	v_pk_mul_f32 v[54:55], v[54:55], v[74:75]
	v_pk_mul_f32 v[64:65], v[64:65], v[68:69]
	v_pk_mul_f32 v[60:61], v[60:61], v[72:73]
	v_pk_mul_f32 v[56:57], v[56:57], v[76:77]
	v_pk_mul_f32 v[52:53], v[52:53], v[80:81]
	v_pk_mul_f32 v[50:51], v[50:51], v[78:79]
	v_pk_mul_f32 v[46:47], v[46:47], v[66:67]
	v_pk_mul_f32 v[42:43], v[42:43], v[70:71]
	v_pk_mul_f32 v[38:39], v[38:39], v[74:75]
	v_pk_mul_f32 v[48:49], v[48:49], v[68:69]
	v_pk_mul_f32 v[44:45], v[44:45], v[72:73]
	v_pk_mul_f32 v[40:41], v[40:41], v[76:77]
	v_pk_mul_f32 v[36:37], v[36:37], v[80:81]
	v_pk_mul_f32 v[34:35], v[34:35], v[78:79]
	v_pk_mul_f32 v[30:31], v[30:31], v[66:67]
	v_pk_mul_f32 v[26:27], v[26:27], v[70:71]
	v_pk_mul_f32 v[22:23], v[22:23], v[74:75]
	v_pk_mul_f32 v[32:33], v[32:33], v[68:69]
	v_pk_mul_f32 v[28:29], v[28:29], v[72:73]
	v_pk_mul_f32 v[24:25], v[24:25], v[76:77]
	v_pk_mul_f32 v[20:21], v[20:21], v[80:81]
	v_pk_mul_f32 v[18:19], v[18:19], v[78:79]
.LBB0_276:
	v_cndmask_b32_e64 v171, v214, v171, s[38:39]
	v_sub_f32_e32 v66, v193, v171
	v_sub_f32_e32 v67, v194, v171
	v_sub_f32_e32 v68, v195, v171
	v_sub_f32_e32 v69, v196, v171
	v_sub_f32_e32 v70, v197, v171
	v_sub_f32_e32 v71, v203, v171
	v_sub_f32_e32 v72, v204, v171
	v_sub_f32_e32 v73, v205, v171
	v_sub_f32_e32 v74, v206, v171
	v_sub_f32_e32 v75, v207, v171
	v_sub_f32_e32 v76, v208, v171
	v_sub_f32_e32 v77, v209, v171
	v_sub_f32_e32 v78, v210, v171
	v_sub_f32_e32 v79, v211, v171
	v_sub_f32_e32 v80, v212, v171
	v_sub_f32_e32 v81, v213, v171
	v_exp_f32_e32 v224, v66
	v_exp_f32_e32 v225, v67
	v_exp_f32_e32 v226, v68
	v_exp_f32_e32 v227, v69
	v_exp_f32_e32 v228, v70
	v_exp_f32_e32 v229, v71
	v_exp_f32_e32 v230, v72
	v_exp_f32_e32 v231, v73
	v_exp_f32_e32 v216, v74
	v_exp_f32_e32 v217, v75
	v_exp_f32_e32 v218, v76
	v_exp_f32_e32 v219, v77
	v_exp_f32_e32 v220, v78
	v_exp_f32_e32 v221, v79
	v_exp_f32_e32 v222, v80
	v_exp_f32_e32 v223, v81
	v_sub_f32_e32 v232, v189, v171
	v_sub_f32_e32 v233, v190, v171
	v_sub_f32_e32 v234, v191, v171
	v_sub_f32_e32 v235, v192, v171
	v_sub_f32_e32 v236, v86, v171
	v_sub_f32_e32 v237, v87, v171
	v_sub_f32_e32 v238, v88, v171
	v_sub_f32_e32 v239, v89, v171
	v_sub_f32_e32 v240, v90, v171
	v_sub_f32_e32 v241, v91, v171
	v_sub_f32_e32 v242, v92, v171
	v_sub_f32_e32 v243, v93, v171
	v_sub_f32_e32 v244, v94, v171
	v_sub_f32_e32 v245, v95, v171
	v_sub_f32_e32 v246, v96, v171
	v_sub_f32_e32 v247, v97, v171
	s_waitcnt lgkmcnt(0)
	s_barrier
	ds_read_b128 v[82:85], v128 offset:32768
	ds_read_b128 v[66:69], v123 offset:32768
	ds_read_b128 v[194:197], v130 offset:32768
	ds_read_b128 v[190:193], v129 offset:32768
	s_cmp_lt_i32 s6, s41
	s_cselect_b64 vcc, -1, 0
	s_waitcnt lgkmcnt(3)
	v_mfma_f32_32x32x16_bf16 v[82:97], v[82:85], v[106:109], 0
	s_waitcnt lgkmcnt(2)
	v_mfma_f32_32x32x16_bf16 v[66:81], v[66:69], v[106:109], 0
	ds_read_b128 v[208:211], v132 offset:32768
	ds_read_b128 v[204:207], v131 offset:32768
	s_waitcnt lgkmcnt(3)
	v_mfma_f32_32x32x16_bf16 v[82:97], v[194:197], v[102:105], v[82:97]
	s_waitcnt lgkmcnt(2)
	v_mfma_f32_32x32x16_bf16 v[66:81], v[190:193], v[102:105], v[66:81]
	ds_read_b128 v[194:197], v134 offset:32768
	ds_read_b128 v[190:193], v133 offset:32768
	s_waitcnt lgkmcnt(3)
	v_mfma_f32_32x32x16_bf16 v[82:97], v[208:211], v[98:101], v[82:97]
	s_waitcnt lgkmcnt(2)
	v_mfma_f32_32x32x16_bf16 v[66:81], v[204:207], v[98:101], v[66:81]
	ds_read_b128 v[204:207], v122
	ds_read_b128 v[212:215], v136 offset:32768
	ds_read_b128 v[208:211], v135 offset:32768
	s_waitcnt lgkmcnt(2)
	v_mfma_f32_32x32x16_bf16 v[82:97], v[194:197], v[204:207], v[82:97]
	v_mfma_f32_32x32x16_bf16 v[66:81], v[190:193], v[204:207], v[66:81]
	ds_read_b128 v[190:193], v138
	ds_read_b128 v[204:207], v140 offset:32768
	ds_read_b128 v[194:197], v139 offset:32768
	s_waitcnt lgkmcnt(2)
	v_mfma_f32_32x32x16_bf16 v[82:97], v[212:215], v[190:193], v[82:97]
	v_mfma_f32_32x32x16_bf16 v[66:81], v[208:211], v[190:193], v[66:81]
	ds_read_b128 v[190:193], v141
	ds_read_b128 v[212:215], v143 offset:32768
	ds_read_b128 v[208:211], v142 offset:32768
	s_waitcnt lgkmcnt(2)
	v_mfma_f32_32x32x16_bf16 v[82:97], v[204:207], v[190:193], v[82:97]
	v_mfma_f32_32x32x16_bf16 v[66:81], v[194:197], v[190:193], v[66:81]
	ds_read_b128 v[190:193], v145
	ds_read_b128 v[204:207], v147 offset:32768
	ds_read_b128 v[194:197], v146 offset:32768
	s_waitcnt lgkmcnt(2)
	v_mfma_f32_32x32x16_bf16 v[82:97], v[212:215], v[190:193], v[82:97]
	v_mfma_f32_32x32x16_bf16 v[66:81], v[208:211], v[190:193], v[66:81]
	ds_read_b128 v[190:193], v148
	ds_read_b128 v[212:215], v156
	ds_read_b128 v[208:211], v155
	s_waitcnt lgkmcnt(2)
	v_mfma_f32_32x32x16_bf16 v[82:97], v[204:207], v[190:193], v[82:97]
	v_mfma_f32_32x32x16_bf16 v[66:81], v[194:197], v[190:193], v[66:81]
	ds_read_b128 v[190:193], v149
	ds_read_b128 v[204:207], v159
	ds_read_b128 v[194:197], v158
	s_waitcnt lgkmcnt(2)
; __device__ __forceinline__ void finishSM(f32x16& p0, f32x16& p1, float alpha, float& l_reg, bf16x8& pa0, bf16x8& pa1, bf16x8& pa2, bf16x8& pa3) {
; #pragma unroll
;   for (int r = 0; r < 16; ++r) p1[r] = __builtin_amdgcn_exp2f(p1[r]);
;   float ps = 0;
; #pragma unroll
;   for (int r = 0; r < 16; ++r) ps += p0[r];
; #pragma unroll
;   for (int r = 0; r < 16; ++r) ps += p1[r];
;   { auto rr = __builtin_amdgcn_permlane32_swap(__float_as_uint(ps), __float_as_uint(ps), false, false);
;     ps = __uint_as_float(rr[0]) + __uint_as_float(rr[1]); }
;   l_reg = l_reg * alpha + ps;
;     ...
;   PK4(p0, 0, pa0); PK4(p0, 8, pa1); PK4(p1, 0, pa2); PK4(p1, 8, pa3);
; template <int MODE>
; __device__ __forceinline__ void qkt(f32x16& p0, f32x16& p1, const char* Ks, const char* K2s, const bf16x8* qr, const char* Q2s, const char* QHs, const char* Q3s, int r32, int hi, bool valid) {
;     ...
;     __builtin_amdgcn_sched_group_barrier(0x100, 2, 0);
; #pragma unroll
;     for (int d = 0; d < ND; ++d) {
;       { const int nrd = ((MODE == 2 && d >= 3) ? 1 : 0) + ((d + 1 < ND) ? 2 : 0);
;         if (nrd == 3) __builtin_amdgcn_sched_group_barrier(0x100, 3, 0); else if (nrd == 2) __builtin_amdgcn_sched_group_barrier(0x100, 2, 0); else if (nrd == 1) __builtin_amdgcn_sched_group_barrier(0x100, 1, 0); }
;       __builtin_amdgcn_sched_group_barrier(0x008, 2, 0);
;     }
;     if constexpr (MODE == 2) {
;       const float msk = valid ? 0.f : -INFINITY;
; #pragma unroll
;       for (int r = 0; r < 16; ++r) { p0[r] = valid ? p0[r] : msk; p1[r] = valid ? p1[r] : msk; }
;     }
	v_mfma_f32_32x32x16_bf16 v[82:97], v[212:215], v[190:193], v[82:97]
	v_mfma_f32_32x32x16_bf16 v[66:81], v[208:211], v[190:193], v[66:81]
	ds_read_b128 v[190:193], v152
	ds_read_b128 v[212:215], v164
	ds_read_b128 v[208:211], v163
	s_waitcnt lgkmcnt(2)
	v_mfma_f32_32x32x16_bf16 v[82:97], v[204:207], v[190:193], v[82:97]
	v_mfma_f32_32x32x16_bf16 v[66:81], v[194:197], v[190:193], v[66:81]
	ds_read_b128 v[190:193], v160
	ds_read_b128 v[204:207], v167
	ds_read_b128 v[194:197], v166
	s_waitcnt lgkmcnt(2)
	v_mfma_f32_32x32x16_bf16 v[82:97], v[212:215], v[190:193], v[82:97]
	v_mfma_f32_32x32x16_bf16 v[66:81], v[208:211], v[190:193], v[66:81]
	ds_read_b128 v[190:193], v161
	s_waitcnt lgkmcnt(0)
	v_mfma_f32_32x32x16_bf16 v[82:97], v[204:207], v[190:193], v[82:97]
	v_mfma_f32_32x32x16_bf16 v[66:81], v[194:197], v[190:193], v[66:81]
	s_nop 10
	v_cndmask_b32_e32 v189, v0, v82, vcc
	v_add_f32_e32 v82, 0, v224
	v_add_f32_e32 v82, v225, v82
	v_add_f32_e32 v82, v226, v82
	v_add_f32_e32 v82, v227, v82
	v_add_f32_e32 v82, v228, v82
	v_add_f32_e32 v82, v229, v82
	v_add_f32_e32 v82, v230, v82
	v_add_f32_e32 v82, v231, v82
	v_add_f32_e32 v82, v216, v82
	v_add_f32_e32 v82, v217, v82
	v_add_f32_e32 v82, v218, v82
	v_add_f32_e32 v82, v219, v82
	v_cndmask_b32_e32 v196, v0, v66, vcc
	v_exp_f32_e32 v66, v232
	v_add_f32_e32 v82, v220, v82
	v_cndmask_b32_e32 v197, v0, v67, vcc
	v_exp_f32_e32 v67, v233
	v_add_f32_e32 v82, v221, v82
	v_cndmask_b32_e32 v203, v0, v68, vcc
	v_exp_f32_e32 v68, v234
	v_add_f32_e32 v82, v222, v82
	v_cndmask_b32_e32 v204, v0, v69, vcc
	v_exp_f32_e32 v69, v235
	v_add_f32_e32 v82, v223, v82
	v_cndmask_b32_e32 v205, v0, v70, vcc
	v_exp_f32_e32 v70, v236
	v_add_f32_e32 v82, v66, v82
	v_cndmask_b32_e32 v206, v0, v71, vcc
	v_exp_f32_e32 v71, v237
	v_add_f32_e32 v82, v67, v82
	v_cndmask_b32_e32 v207, v0, v72, vcc
	v_exp_f32_e32 v72, v238
	v_add_f32_e32 v82, v68, v82
	v_cndmask_b32_e32 v208, v0, v73, vcc
	v_exp_f32_e32 v73, v239
	v_add_f32_e32 v82, v69, v82
	v_cndmask_b32_e32 v209, v0, v74, vcc
	v_exp_f32_e32 v74, v240
	v_add_f32_e32 v82, v70, v82
	v_cndmask_b32_e32 v210, v0, v75, vcc
	v_exp_f32_e32 v75, v241
	v_add_f32_e32 v82, v71, v82
	v_cndmask_b32_e32 v211, v0, v76, vcc
	v_exp_f32_e32 v76, v242
	v_add_f32_e32 v82, v72, v82
	v_cndmask_b32_e32 v212, v0, v77, vcc
	v_exp_f32_e32 v77, v243
	v_add_f32_e32 v82, v73, v82
	v_cndmask_b32_e32 v213, v0, v78, vcc
	v_exp_f32_e32 v78, v244
	v_add_f32_e32 v82, v74, v82
	v_cndmask_b32_e32 v214, v0, v79, vcc
	v_exp_f32_e32 v79, v245
	v_add_f32_e32 v82, v75, v82
	v_cndmask_b32_e32 v193, v0, v86, vcc
	v_cndmask_b32_e32 v86, v0, v95, vcc
	v_cndmask_b32_e32 v95, v0, v80, vcc
	v_exp_f32_e32 v80, v246
	v_add_f32_e32 v82, v76, v82
	v_cndmask_b32_e32 v194, v0, v87, vcc
	v_cndmask_b32_e32 v87, v0, v96, vcc
	v_cndmask_b32_e32 v96, v0, v81, vcc
	v_exp_f32_e32 v81, v247
	v_add_f32_e32 v82, v77, v82
	v_add_f32_e32 v82, v78, v82
	v_add_f32_e32 v82, v79, v82
	v_add_f32_e32 v82, v80, v82
	v_cndmask_b32_e32 v195, v0, v88, vcc
	v_cndmask_b32_e32 v88, v0, v97, vcc
	v_add_f32_e32 v97, v81, v82
	v_mov_b32_e32 v215, v97
	v_cndmask_b32_e32 v190, v0, v83, vcc
	v_cndmask_b32_e32 v191, v0, v84, vcc
	v_cndmask_b32_e32 v192, v0, v85, vcc
	v_cndmask_b32_e32 v89, v0, v89, vcc
	v_cndmask_b32_e32 v90, v0, v90, vcc
	v_cndmask_b32_e32 v91, v0, v91, vcc
	v_cndmask_b32_e32 v92, v0, v92, vcc
	v_cndmask_b32_e32 v93, v0, v93, vcc
	v_cndmask_b32_e32 v94, v0, v94, vcc
	v_permlane32_swap_b32_e32 v97, v215
	v_cvt_pk_bf16_f32 v224, v224, v225
	v_cvt_pk_bf16_f32 v225, v226, v227
	v_cvt_pk_bf16_f32 v226, v228, v229
	v_cvt_pk_bf16_f32 v227, v230, v231
	v_cvt_pk_bf16_f32 v216, v216, v217
	v_cvt_pk_bf16_f32 v217, v218, v219
	v_cvt_pk_bf16_f32 v218, v220, v221
	v_cvt_pk_bf16_f32 v219, v222, v223
	v_cvt_pk_bf16_f32 v220, v66, v67
	v_cvt_pk_bf16_f32 v221, v68, v69
	v_cvt_pk_bf16_f32 v222, v70, v71
	v_cvt_pk_bf16_f32 v223, v72, v73
	v_cvt_pk_bf16_f32 v228, v74, v75
	v_cvt_pk_bf16_f32 v229, v76, v77
	v_cvt_pk_bf16_f32 v230, v78, v79
	v_cvt_pk_bf16_f32 v231, v80, v81
	v_permlane32_swap_b32_e32 v224, v226
	v_permlane32_swap_b32_e32 v225, v227
	v_permlane32_swap_b32_e32 v216, v218
	v_permlane32_swap_b32_e32 v217, v219
	v_permlane32_swap_b32_e32 v220, v222
	v_permlane32_swap_b32_e32 v221, v223
	v_permlane32_swap_b32_e32 v228, v230
	v_permlane32_swap_b32_e32 v229, v231
	s_mov_b32 s4, 0x2b8c0000
	v_add_co_u32_e32 v70, vcc, s4, v114
	s_mov_b32 s4, 0x2b8e0000
	s_nop 0
	v_addc_co_u32_e32 v71, vcc, 0, v115, vcc
	v_add_co_u32_e32 v74, vcc, s4, v114
	s_mov_b32 s4, 0x1206000
	s_nop 0
	v_addc_co_u32_e32 v75, vcc, 0, v115, vcc
	v_add_co_u32_e32 v82, vcc, s4, v116
	global_load_dwordx4 v[66:69], v[70:71], off offset:2048
	s_nop 0
	v_addc_co_u32_e32 v83, vcc, 0, v117, vcc
	global_load_dwordx4 v[70:73], v[70:71], off
	s_nop 0
	global_load_dwordx4 v[78:81], v[74:75], off offset:2048
	s_nop 0
	global_load_dwordx4 v[74:77], v[74:75], off
	s_nop 0
	global_load_dwordx4 v[82:85], v[82:83], off
	ds_read_b64_tr_b16 v[114:115], v121 offset:0
	ds_read_b64_tr_b16 v[116:117], v121 offset:0x800
	ds_read_b64_tr_b16 v[232:233], v121 offset:0x1000
	ds_read_b64_tr_b16 v[234:235], v121 offset:0x1800
	ds_read_b64_tr_b16 v[236:237], v121 offset:0x2000
	ds_read_b64_tr_b16 v[238:239], v121 offset:0x2800
	ds_read_b64_tr_b16 v[240:241], v121 offset:0x3000
	ds_read_b64_tr_b16 v[242:243], v121 offset:0x3800
	s_waitcnt lgkmcnt(0)
; #define SBAR() __builtin_amdgcn_sched_barrier(0)
; __device__ __forceinline__ void partialSM(f32x16& p0, f32x16& p1, float& m_reg, float& mn, float& alpha) {
;   float pmax = p0[0];
; #pragma unroll
;   for (int r = 1; r < 16; ++r) pmax = fmaxf(pmax, p0[r]);
; #pragma unroll
;   for (int r = 0; r < 16; ++r) pmax = fmaxf(pmax, p1[r]);
;   { auto rr = __builtin_amdgcn_permlane32_swap(__float_as_uint(pmax), __float_as_uint(pmax), false, false);
;     pmax = fmaxf(__uint_as_float(rr[0]), __uint_as_float(rr[1])); }
;   if (__builtin_expect(__all(pmax - m_reg <= THR), 1)) { mn = m_reg; alpha = 1.f; }
;   else { mn = fmaxf(m_reg, pmax); alpha = __builtin_amdgcn_exp2f(m_reg - mn); m_reg = mn; }
; template <int D0> __device__ __forceinline__ void pv_one(f32x16& od, int vb, bf16x8 pa0, bf16x8 pa1, bf16x8 pa2, bf16x8 pa3) {
;   const s16x4 l0 = tr_read<v_rd_off(D0, 0, 0)>(vb), h0 = tr_read<v_rd_off(D0, 0, 1)>(vb), l1 = tr_read<v_rd_off(D0, 1, 0)>(vb), h1 = tr_read<v_rd_off(D0, 1, 1)>(vb);
;   const s16x4 l2 = tr_read<v_rd_off(D0, 2, 0)>(vb), h2 = tr_read<v_rd_off(D0, 2, 1)>(vb), l3 = tr_read<v_rd_off(D0, 3, 0)>(vb), h3 = tr_read<v_rd_off(D0, 3, 1)>(vb);
;   asm volatile("s_waitcnt lgkmcnt(0)" ::: "memory"); SBAR();
;     ...
;   od = __builtin_amdgcn_mfma_f32_32x32x16_bf16(pa0, PK(l0, h0), od, 0, 0, 0);
;   od = __builtin_amdgcn_mfma_f32_32x32x16_bf16(pa1, PK(l1, h1), od, 0, 0, 0);
;   od = __builtin_amdgcn_mfma_f32_32x32x16_bf16(pa2, PK(l2, h2), od, 0, 0, 0);
;   od = __builtin_amdgcn_mfma_f32_32x32x16_bf16(pa3, PK(l3, h3), od, 0, 0, 0);
;     ...
; }
; __device__ __forceinline__ void pv_d0(f32x16* o, int vb, bf16x8 pa0, bf16x8 pa1, bf16x8 pa2, bf16x8 pa3) {
;   pv_one<0>(o[0], vb, pa0, pa1, pa2, pa3); pv_one<1>(o[1], vb, pa0, pa1, pa2, pa3); pv_one<2>(o[2], vb, pa0, pa1, pa2, pa3); pv_one<3>(o[3], vb, pa0, pa1, pa2, pa3);
	s_nop 0
	v_mfma_f32_32x32x16_bf16 v[2:17], v[224:227], v[114:117], v[2:17]
	ds_read_b64_tr_b16 v[114:115], v121 offset:0x200
	ds_read_b64_tr_b16 v[116:117], v121 offset:0xa00
	v_mfma_f32_32x32x16_bf16 v[2:17], v[216:219], v[232:235], v[2:17]
	ds_read_b64_tr_b16 v[232:233], v121 offset:0x1200
	ds_read_b64_tr_b16 v[234:235], v121 offset:0x1a00
	v_mfma_f32_32x32x16_bf16 v[2:17], v[220:223], v[236:239], v[2:17]
	ds_read_b64_tr_b16 v[236:237], v121 offset:0x2200
	ds_read_b64_tr_b16 v[238:239], v121 offset:0x2a00
	v_mfma_f32_32x32x16_bf16 v[2:17], v[228:231], v[240:243], v[2:17]
	ds_read_b64_tr_b16 v[240:241], v121 offset:0x3200
	ds_read_b64_tr_b16 v[242:243], v121 offset:0x3a00
	s_waitcnt lgkmcnt(0)
	v_mfma_f32_32x32x16_bf16 v[50:65], v[224:227], v[114:117], v[50:65]
	ds_read_b64_tr_b16 v[114:115], v121 offset:0x400
	ds_read_b64_tr_b16 v[116:117], v121 offset:0xc00
	v_mfma_f32_32x32x16_bf16 v[50:65], v[216:219], v[232:235], v[50:65]
	ds_read_b64_tr_b16 v[232:233], v121 offset:0x1400
	ds_read_b64_tr_b16 v[234:235], v121 offset:0x1c00
	v_mfma_f32_32x32x16_bf16 v[50:65], v[220:223], v[236:239], v[50:65]
	ds_read_b64_tr_b16 v[236:237], v121 offset:0x2400
	ds_read_b64_tr_b16 v[238:239], v121 offset:0x2c00
	v_mfma_f32_32x32x16_bf16 v[50:65], v[228:231], v[240:243], v[50:65]
	ds_read_b64_tr_b16 v[240:241], v121 offset:0x3400
	ds_read_b64_tr_b16 v[242:243], v121 offset:0x3c00
	s_waitcnt lgkmcnt(0)
	v_mfma_f32_32x32x16_bf16 v[34:49], v[224:227], v[114:117], v[34:49]
	ds_read_b64_tr_b16 v[114:115], v121 offset:0x600
	ds_read_b64_tr_b16 v[116:117], v121 offset:0xe00
	v_mfma_f32_32x32x16_bf16 v[34:49], v[216:219], v[232:235], v[34:49]
	ds_read_b64_tr_b16 v[232:233], v121 offset:0x1600
	ds_read_b64_tr_b16 v[234:235], v121 offset:0x1e00
	v_mfma_f32_32x32x16_bf16 v[34:49], v[220:223], v[236:239], v[34:49]
	ds_read_b64_tr_b16 v[236:237], v121 offset:0x2600
	ds_read_b64_tr_b16 v[238:239], v121 offset:0x2e00
	v_mfma_f32_32x32x16_bf16 v[34:49], v[228:231], v[240:243], v[34:49]
	ds_read_b64_tr_b16 v[240:241], v121 offset:0x3600
	ds_read_b64_tr_b16 v[242:243], v121 offset:0x3e00
	s_waitcnt lgkmcnt(0)
	v_mfma_f32_32x32x16_bf16 v[18:33], v[224:227], v[114:117], v[18:33]
	v_max_f32_e32 v114, v196, v197
	v_max3_f32 v114, v114, v203, v204
	v_max3_f32 v114, v114, v205, v206
	v_max3_f32 v114, v114, v207, v208
	v_max3_f32 v114, v114, v209, v210
	v_max3_f32 v114, v114, v211, v212
	v_mfma_f32_32x32x16_bf16 v[18:33], v[216:219], v[232:235], v[18:33]
	v_max3_f32 v114, v114, v213, v214
	v_max3_f32 v114, v114, v95, v96
	v_max3_f32 v114, v114, v189, v190
	v_max3_f32 v114, v114, v191, v192
	v_max3_f32 v114, v114, v193, v194
	v_max3_f32 v114, v114, v195, v89
	v_max3_f32 v114, v114, v90, v91
	v_max3_f32 v114, v114, v92, v93
	v_mfma_f32_32x32x16_bf16 v[18:33], v[220:223], v[236:239], v[18:33]
	v_max3_f32 v114, v114, v94, v86
	v_max3_f32 v114, v114, v87, v88
	v_mov_b32_e32 v115, v114
	s_nop 1
	v_permlane32_swap_b32_e32 v114, v115
	v_max_f32_e32 v114, v114, v115
	v_sub_f32_e32 v115, v114, v171
	v_cmp_ge_f32_e32 vcc, s58, v115
	v_mfma_f32_32x32x16_bf16 v[18:33], v[228:231], v[240:243], v[18:33]
	v_max_f32_e32 v115, v171, v114
	v_sub_f32_e32 v114, v171, v115
	v_exp_f32_e32 v114, v114
	s_cmp_eq_u64 vcc, exec
	s_cselect_b64 s[38:39], -1, 0
	s_barrier
	s_waitcnt vmcnt(0)
	v_cndmask_b32_e64 v114, v114, 1.0, s[38:39]
	v_cmp_gt_f32_e32 vcc, 1.0, v114
	s_waitcnt vmcnt(4)
	ds_write_b128 v126, v[66:69] offset:16384
	s_waitcnt vmcnt(2)
	ds_write_b128 v127, v[78:81] offset:16384
	ds_write_b128 v124, v[70:73] offset:49152
	s_waitcnt vmcnt(1)
	ds_write_b128 v125, v[74:77] offset:49152
	s_waitcnt vmcnt(0)
	ds_write_b128 v170, v[82:85]
	s_cbranch_vccz .LBB0_280
	s_and_saveexec_b64 s[4:5], s[36:37]
	ds_write_b32 v119, v114 offset:128
	s_or_b64 exec, exec, s[4:5]
	s_waitcnt lgkmcnt(0)
	v_add_u32_e32 v78, s22, v174
	ds_read_b128 v[66:69], v78 offset:224
	ds_read_b128 v[70:73], v78 offset:192
	ds_read_b128 v[74:77], v78 offset:160
	ds_read_b128 v[78:81], v78 offset:128
	s_waitcnt lgkmcnt(3)
	v_pk_mul_f32 v[14:15], v[14:15], v[66:67]
	s_waitcnt lgkmcnt(2)
	v_pk_mul_f32 v[10:11], v[10:11], v[70:71]
	s_waitcnt lgkmcnt(1)
	v_pk_mul_f32 v[6:7], v[6:7], v[74:75]
	v_pk_mul_f32 v[16:17], v[16:17], v[68:69]
	v_pk_mul_f32 v[12:13], v[12:13], v[72:73]
	v_pk_mul_f32 v[8:9], v[8:9], v[76:77]
	s_waitcnt lgkmcnt(0)
	v_pk_mul_f32 v[4:5], v[4:5], v[80:81]
	v_pk_mul_f32 v[2:3], v[2:3], v[78:79]
	v_pk_mul_f32 v[62:63], v[62:63], v[66:67]
	v_pk_mul_f32 v[58:59], v[58:59], v[70:71]
	v_pk_mul_f32 v[54:55], v[54:55], v[74:75]
	v_pk_mul_f32 v[64:65], v[64:65], v[68:69]
	v_pk_mul_f32 v[60:61], v[60:61], v[72:73]
	v_pk_mul_f32 v[56:57], v[56:57], v[76:77]
	v_pk_mul_f32 v[52:53], v[52:53], v[80:81]
	v_pk_mul_f32 v[50:51], v[50:51], v[78:79]
	v_pk_mul_f32 v[46:47], v[46:47], v[66:67]
	v_pk_mul_f32 v[42:43], v[42:43], v[70:71]
	v_pk_mul_f32 v[38:39], v[38:39], v[74:75]
	v_pk_mul_f32 v[48:49], v[48:49], v[68:69]
	v_pk_mul_f32 v[44:45], v[44:45], v[72:73]
	v_pk_mul_f32 v[40:41], v[40:41], v[76:77]
	v_pk_mul_f32 v[36:37], v[36:37], v[80:81]
	v_pk_mul_f32 v[34:35], v[34:35], v[78:79]
	v_pk_mul_f32 v[30:31], v[30:31], v[66:67]
	v_pk_mul_f32 v[26:27], v[26:27], v[70:71]
	v_pk_mul_f32 v[22:23], v[22:23], v[74:75]
	v_pk_mul_f32 v[32:33], v[32:33], v[68:69]
	v_pk_mul_f32 v[28:29], v[28:29], v[72:73]
	v_pk_mul_f32 v[24:25], v[24:25], v[76:77]
	v_pk_mul_f32 v[20:21], v[20:21], v[80:81]
	v_pk_mul_f32 v[18:19], v[18:19], v[78:79]

; #define SBAR() __builtin_amdgcn_sched_barrier(0)
; #define KFRAG(d, hf) (((d) < 8) ? *reinterpret_cast<const bf16x8*>(Ks + KSWZ((hf) * 32 + r32, ((d) * 16 + hi * 8) * 2)) \
;                                 : *reinterpret_cast<const bf16x8*>(K2s + K2SWZ((hf) * 32 + r32, (((d) - 8) * 16 + hi * 8) * 2)))
; #define QLDS(d) (((d) == 3) ? *reinterpret_cast<const bf16x8*>(Q3s) : ((d) < 8) ? *reinterpret_cast<const bf16x8*>(QHs + K2SWZ(r32, (((d) - 4) * 16 + hi * 8) * 2)) \
;                            : *reinterpret_cast<const bf16x8*>(Q2s + K2SWZ(r32, (((d) - 8) * 16 + hi * 8) * 2)))
; template <int MODE>
; __device__ __forceinline__ void qkt(f32x16& p0, f32x16& p1, const char* Ks, const char* K2s, const bf16x8* qr, const char* Q2s, const char* QHs, const char* Q3s, int r32, int hi, bool valid) {
;     ...
;     p0 = f32x16{}; p1 = f32x16{};
;     constexpr int ND = (MODE == 2) ? 12 : 8;
;     bf16x8 ka[2], kb[2];
;     ka[0] = KFRAG(0, 0); kb[0] = KFRAG(0, 1);
; #pragma unroll
;     for (int d = 0; d < ND; ++d) {
;       bf16x8 q; if (MODE == 2 && d >= 3) q = QLDS(d); else q = qr[d < 8 ? d : 0];
;       if (d + 1 < ND) { ka[(d + 1) & 1] = KFRAG(d + 1, 0); kb[(d + 1) & 1] = KFRAG(d + 1, 1); }
;       p0 = __builtin_amdgcn_mfma_f32_32x32x16_bf16(ka[d & 1], q, p0, 0, 0, 0);
;       p1 = __builtin_amdgcn_mfma_f32_32x32x16_bf16(kb[d & 1], q, p1, 0, 0, 0);
;     }
;     __builtin_amdgcn_sched_group_barrier(0x100, 2, 0);
; #pragma unroll
;     for (int d = 0; d < ND; ++d) {
;       { const int nrd = ((MODE == 2 && d >= 3) ? 1 : 0) + ((d + 1 < ND) ? 2 : 0);
;         if (nrd == 3) __builtin_amdgcn_sched_group_barrier(0x100, 3, 0); else if (nrd == 2) __builtin_amdgcn_sched_group_barrier(0x100, 2, 0); else if (nrd == 1) __builtin_amdgcn_sched_group_barrier(0x100, 1, 0); }
;       __builtin_amdgcn_sched_group_barrier(0x008, 2, 0);
;     }
;     if constexpr (MODE == 2) {
;       const float msk = valid ? 0.f : -INFINITY;
; #pragma unroll
;       for (int r = 0; r < 16; ++r) { p0[r] = valid ? p0[r] : msk; p1[r] = valid ? p1[r] : msk; }
;     }
; template <int MODE> ...
;     ...
;   SBAR(); QKT(pB0, pB1, 1, NT - 1);
;   finishSM(pA0, pA1, alA, l_reg, pa0, pa1, pa2, pa3); SBAR();
;   if (MODE != 1 || VALID(NT - 2)) pv_d0(o, vb0, pa0, pa1, pa2, pa3);
.LBB0_282:
	ds_read_b128 v[66:69], v123 offset:49152
	ds_read_b128 v[82:85], v128 offset:49152
	ds_read_b128 v[110:113], v129 offset:49152
	ds_read_b128 v[124:127], v130 offset:49152
	s_cmp_lt_i32 s23, 3
	s_cselect_b64 vcc, -1, 0
	s_waitcnt lgkmcnt(3)
	v_mfma_f32_32x32x16_bf16 v[66:81], v[66:69], v[106:109], 0
	s_waitcnt lgkmcnt(2)
	v_mfma_f32_32x32x16_bf16 v[82:97], v[82:85], v[106:109], 0
	ds_read_b128 v[106:109], v131 offset:49152
	ds_read_b128 v[128:131], v132 offset:49152
	v_exp_f32_e32 v132, v241
	s_waitcnt lgkmcnt(3)
	v_mfma_f32_32x32x16_bf16 v[66:81], v[110:113], v[102:105], v[66:81]
	s_waitcnt lgkmcnt(2)
	v_mfma_f32_32x32x16_bf16 v[82:97], v[124:127], v[102:105], v[82:97]
	ds_read_b128 v[102:105], v133 offset:49152
	ds_read_b128 v[110:113], v134 offset:49152
	v_exp_f32_e32 v126, v237
	v_exp_f32_e32 v127, v238
	s_waitcnt lgkmcnt(3)
	v_mfma_f32_32x32x16_bf16 v[66:81], v[106:109], v[98:101], v[66:81]
	s_waitcnt lgkmcnt(2)
	v_mfma_f32_32x32x16_bf16 v[82:97], v[128:131], v[98:101], v[82:97]
	ds_read_b128 v[98:101], v122
	ds_read_b128 v[106:109], v135 offset:49152
	ds_read_b128 v[122:125], v136 offset:49152
	v_exp_f32_e32 v128, v239
	v_exp_f32_e32 v129, v240
	v_exp_f32_e32 v130, v242
	v_exp_f32_e32 v131, v243
	s_waitcnt lgkmcnt(2)
	v_mfma_f32_32x32x16_bf16 v[66:81], v[102:105], v[98:101], v[66:81]
	v_mfma_f32_32x32x16_bf16 v[82:97], v[110:113], v[98:101], v[82:97]
	ds_read_b128 v[98:101], v138
	ds_read_b128 v[102:105], v139 offset:49152
	ds_read_b128 v[110:113], v140 offset:49152
	s_waitcnt lgkmcnt(2)
	v_mfma_f32_32x32x16_bf16 v[66:81], v[106:109], v[98:101], v[66:81]
	v_mfma_f32_32x32x16_bf16 v[82:97], v[122:125], v[98:101], v[82:97]
	ds_read_b128 v[98:101], v141
	ds_read_b128 v[106:109], v142 offset:49152
	ds_read_b128 v[122:125], v143 offset:49152
	s_waitcnt lgkmcnt(2)
	v_mfma_f32_32x32x16_bf16 v[66:81], v[102:105], v[98:101], v[66:81]
	v_mfma_f32_32x32x16_bf16 v[82:97], v[110:113], v[98:101], v[82:97]
	ds_read_b128 v[98:101], v145
	ds_read_b128 v[102:105], v146 offset:49152
	ds_read_b128 v[110:113], v147 offset:49152
	s_waitcnt lgkmcnt(2)
	v_mfma_f32_32x32x16_bf16 v[66:81], v[106:109], v[98:101], v[66:81]
	v_mfma_f32_32x32x16_bf16 v[82:97], v[122:125], v[98:101], v[82:97]
	ds_read_b128 v[98:101], v148
	ds_read_b128 v[106:109], v172
	ds_read_b128 v[122:125], v173
	s_waitcnt lgkmcnt(2)
	v_mfma_f32_32x32x16_bf16 v[66:81], v[102:105], v[98:101], v[66:81]
	v_mfma_f32_32x32x16_bf16 v[82:97], v[110:113], v[98:101], v[82:97]
	ds_read_b128 v[98:101], v149
	ds_read_b128 v[102:105], v176
	ds_read_b128 v[110:113], v177
	s_waitcnt lgkmcnt(2)
	v_mfma_f32_32x32x16_bf16 v[66:81], v[106:109], v[98:101], v[66:81]
	v_mfma_f32_32x32x16_bf16 v[82:97], v[122:125], v[98:101], v[82:97]
	ds_read_b128 v[98:101], v152
	ds_read_b128 v[106:109], v182
	ds_read_b128 v[122:125], v183
	s_waitcnt lgkmcnt(2)
	v_mfma_f32_32x32x16_bf16 v[66:81], v[102:105], v[98:101], v[66:81]
	v_mfma_f32_32x32x16_bf16 v[82:97], v[110:113], v[98:101], v[82:97]
	ds_read_b128 v[98:101], v160
	ds_read_b128 v[102:105], v184
	ds_read_b128 v[110:113], v185
	s_waitcnt lgkmcnt(2)
	v_mfma_f32_32x32x16_bf16 v[66:81], v[106:109], v[98:101], v[66:81]
	v_cvt_pk_bf16_f32 v106, v115, v116
	v_cvt_pk_bf16_f32 v107, v117, v214
	v_cvt_pk_bf16_f32 v108, v216, v217
	v_cvt_pk_bf16_f32 v109, v218, v219
	s_nop 0
	v_permlane32_swap_b32_e32 v106, v108
	v_permlane32_swap_b32_e32 v107, v109
	v_mfma_f32_32x32x16_bf16 v[82:97], v[122:125], v[98:101], v[82:97]
	ds_read_b128 v[98:101], v161
	v_exp_f32_e32 v122, v233
	v_exp_f32_e32 v123, v234
	v_exp_f32_e32 v124, v235
	v_exp_f32_e32 v125, v236
	s_waitcnt lgkmcnt(0)
	v_mfma_f32_32x32x16_bf16 v[66:81], v[102:105], v[98:101], v[66:81]
	v_cvt_pk_bf16_f32 v102, v220, v221
	v_cvt_pk_bf16_f32 v103, v222, v223
	v_cvt_pk_bf16_f32 v104, v224, v225
	v_cvt_pk_bf16_f32 v105, v226, v227
	s_nop 0
	v_permlane32_swap_b32_e32 v102, v104
	v_permlane32_swap_b32_e32 v103, v105
	v_mfma_f32_32x32x16_bf16 v[82:97], v[110:113], v[98:101], v[82:97]
	s_nop 3
	v_cndmask_b32_e32 v98, v66, v0, vcc
	v_add_f32_e32 v66, 0, v220
	v_add_f32_e32 v66, v221, v66
	v_add_f32_e32 v66, v222, v66
	v_add_f32_e32 v66, v223, v66
	v_add_f32_e32 v66, v224, v66
	v_add_f32_e32 v66, v225, v66
	v_add_f32_e32 v66, v226, v66
	v_add_f32_e32 v66, v227, v66
	v_add_f32_e32 v66, v115, v66
	v_add_f32_e32 v66, v116, v66
	v_add_f32_e32 v66, v117, v66
	v_add_f32_e32 v66, v214, v66
	v_cndmask_b32_e32 v100, v68, v0, vcc
	v_cndmask_b32_e32 v68, v84, v0, vcc
	v_cndmask_b32_e32 v84, v69, v0, vcc
	v_cndmask_b32_e32 v69, v85, v0, vcc
	v_cndmask_b32_e32 v85, v70, v0, vcc
	v_cndmask_b32_e32 v70, v86, v0, vcc
	v_cndmask_b32_e32 v86, v71, v0, vcc
	v_cndmask_b32_e32 v71, v87, v0, vcc
	v_cndmask_b32_e32 v87, v72, v0, vcc
	v_cndmask_b32_e32 v72, v88, v0, vcc
	v_cndmask_b32_e32 v88, v73, v0, vcc
	v_cndmask_b32_e32 v73, v89, v0, vcc
	v_cndmask_b32_e32 v89, v74, v0, vcc
	v_cndmask_b32_e32 v74, v90, v0, vcc
	v_cndmask_b32_e32 v90, v75, v0, vcc
	v_cndmask_b32_e32 v75, v91, v0, vcc
	v_cndmask_b32_e32 v91, v76, v0, vcc
	v_cndmask_b32_e32 v76, v92, v0, vcc
	v_cndmask_b32_e32 v92, v77, v0, vcc
	v_cndmask_b32_e32 v77, v93, v0, vcc
	v_cndmask_b32_e32 v93, v78, v0, vcc
	v_cndmask_b32_e32 v78, v94, v0, vcc
	v_cndmask_b32_e32 v94, v79, v0, vcc
	v_cndmask_b32_e32 v79, v95, v0, vcc
	v_cndmask_b32_e32 v95, v80, v0, vcc
	v_cndmask_b32_e32 v80, v96, v0, vcc
	v_cndmask_b32_e32 v96, v81, v0, vcc
	v_cndmask_b32_e32 v81, v97, v0, vcc
	v_exp_f32_e32 v97, v228
	v_add_f32_e32 v66, v216, v66
	v_exp_f32_e32 v101, v229
	v_add_f32_e32 v66, v217, v66
	v_exp_f32_e32 v111, v230
	v_add_f32_e32 v66, v218, v66
	v_exp_f32_e32 v112, v231
	v_add_f32_e32 v66, v219, v66
; __device__ __forceinline__ void partialSM(f32x16& p0, f32x16& p1, float& m_reg, float& mn, float& alpha) {
;   float pmax = p0[0];
; #pragma unroll
;   for (int r = 1; r < 16; ++r) pmax = fmaxf(pmax, p0[r]);
; #pragma unroll
;   for (int r = 0; r < 16; ++r) pmax = fmaxf(pmax, p1[r]);
;   { auto rr = __builtin_amdgcn_permlane32_swap(__float_as_uint(pmax), __float_as_uint(pmax), false, false);
;     pmax = fmaxf(__uint_as_float(rr[0]), __uint_as_float(rr[1])); }
;   if (__builtin_expect(__all(pmax - m_reg <= THR), 1)) { mn = m_reg; alpha = 1.f; }
;   else { mn = fmaxf(m_reg, pmax); alpha = __builtin_amdgcn_exp2f(m_reg - mn); m_reg = mn; }
; __device__ __forceinline__ void finishSM(f32x16& p0, f32x16& p1, float alpha, float& l_reg, bf16x8& pa0, bf16x8& pa1, bf16x8& pa2, bf16x8& pa3) {
; #pragma unroll
;   for (int r = 0; r < 16; ++r) p1[r] = __builtin_amdgcn_exp2f(p1[r]);
;   float ps = 0;
; #pragma unroll
;   for (int r = 0; r < 16; ++r) ps += p0[r];
; #pragma unroll
;   for (int r = 0; r < 16; ++r) ps += p1[r];
;   { auto rr = __builtin_amdgcn_permlane32_swap(__float_as_uint(ps), __float_as_uint(ps), false, false);
;     ps = __uint_as_float(rr[0]) + __uint_as_float(rr[1]); }
;   l_reg = l_reg * alpha + ps;
;     ...
;   PK4(p0, 0, pa0); PK4(p0, 8, pa1); PK4(p1, 0, pa2); PK4(p1, 8, pa3);
	v_exp_f32_e32 v113, v232
	v_add_f32_e32 v66, v97, v66
	v_add_f32_e32 v66, v101, v66
	v_add_f32_e32 v66, v111, v66
	v_add_f32_e32 v66, v112, v66
	v_add_f32_e32 v66, v113, v66
	v_add_f32_e32 v66, v122, v66
	v_add_f32_e32 v66, v123, v66
	v_add_f32_e32 v66, v124, v66
	v_add_f32_e32 v66, v125, v66
	v_add_f32_e32 v66, v126, v66
	v_add_f32_e32 v66, v127, v66
	v_add_f32_e32 v66, v128, v66
	v_add_f32_e32 v66, v129, v66
	v_add_f32_e32 v66, v130, v66
	v_add_f32_e32 v66, v131, v66
	v_add_f32_e32 v66, v132, v66
	v_cndmask_b32_e32 v99, v67, v0, vcc
	v_mov_b32_e32 v67, v66
	v_cndmask_b32_e32 v82, v82, v0, vcc
	v_cndmask_b32_e32 v83, v83, v0, vcc
	v_permlane32_swap_b32_e32 v66, v67
	v_cvt_pk_bf16_f32 v110, v97, v101
	v_cvt_pk_bf16_f32 v111, v111, v112
	v_cvt_pk_bf16_f32 v112, v113, v122
	v_cvt_pk_bf16_f32 v113, v123, v124
	v_cvt_pk_bf16_f32 v122, v125, v126
	v_cvt_pk_bf16_f32 v123, v127, v128
	v_cvt_pk_bf16_f32 v124, v129, v130
	v_cvt_pk_bf16_f32 v125, v131, v132
	v_permlane32_swap_b32_e32 v110, v112
	v_permlane32_swap_b32_e32 v111, v113
	v_permlane32_swap_b32_e32 v122, v124
	v_permlane32_swap_b32_e32 v123, v125
	ds_read_b64_tr_b16 v[126:127], v137 offset:0
	ds_read_b64_tr_b16 v[128:129], v137 offset:0x800
	ds_read_b64_tr_b16 v[130:131], v137 offset:0x1000
	ds_read_b64_tr_b16 v[132:133], v137 offset:0x1800
	ds_read_b64_tr_b16 v[138:139], v137 offset:0x2000
	ds_read_b64_tr_b16 v[140:141], v137 offset:0x2800
	ds_read_b64_tr_b16 v[142:143], v137 offset:0x3000
	ds_read_b64_tr_b16 v[144:145], v137 offset:0x3800
	s_waitcnt lgkmcnt(0)
	s_nop 0
	v_mfma_f32_32x32x16_bf16 v[2:17], v[102:105], v[126:129], v[2:17]
	ds_read_b64_tr_b16 v[126:127], v137 offset:0x200
	ds_read_b64_tr_b16 v[128:129], v137 offset:0xa00
	v_mfma_f32_32x32x16_bf16 v[2:17], v[106:109], v[130:133], v[2:17]
	ds_read_b64_tr_b16 v[130:131], v137 offset:0x1200
	ds_read_b64_tr_b16 v[132:133], v137 offset:0x1a00
	v_mfma_f32_32x32x16_bf16 v[2:17], v[110:113], v[138:141], v[2:17]
	ds_read_b64_tr_b16 v[138:139], v137 offset:0x2200
	ds_read_b64_tr_b16 v[140:141], v137 offset:0x2a00
	v_mfma_f32_32x32x16_bf16 v[2:17], v[122:125], v[142:145], v[2:17]
	ds_read_b64_tr_b16 v[142:143], v137 offset:0x3200
	ds_read_b64_tr_b16 v[144:145], v137 offset:0x3a00
	s_waitcnt lgkmcnt(0)
	v_mfma_f32_32x32x16_bf16 v[50:65], v[102:105], v[126:129], v[50:65]
	ds_read_b64_tr_b16 v[126:127], v137 offset:0x400
	ds_read_b64_tr_b16 v[128:129], v137 offset:0xc00
	v_mfma_f32_32x32x16_bf16 v[50:65], v[106:109], v[130:133], v[50:65]
	ds_read_b64_tr_b16 v[130:131], v137 offset:0x1400
	ds_read_b64_tr_b16 v[132:133], v137 offset:0x1c00
	v_mfma_f32_32x32x16_bf16 v[50:65], v[110:113], v[138:141], v[50:65]
	ds_read_b64_tr_b16 v[138:139], v137 offset:0x2400
	ds_read_b64_tr_b16 v[140:141], v137 offset:0x2c00
	v_mfma_f32_32x32x16_bf16 v[50:65], v[122:125], v[142:145], v[50:65]
	ds_read_b64_tr_b16 v[142:143], v137 offset:0x3400
	ds_read_b64_tr_b16 v[144:145], v137 offset:0x3c00
	s_waitcnt lgkmcnt(0)
	v_mfma_f32_32x32x16_bf16 v[34:49], v[102:105], v[126:129], v[34:49]
	ds_read_b64_tr_b16 v[126:127], v137 offset:0x600
	ds_read_b64_tr_b16 v[128:129], v137 offset:0xe00
	v_mfma_f32_32x32x16_bf16 v[34:49], v[106:109], v[130:133], v[34:49]
	ds_read_b64_tr_b16 v[130:131], v137 offset:0x1600
	ds_read_b64_tr_b16 v[132:133], v137 offset:0x1e00
	v_mfma_f32_32x32x16_bf16 v[34:49], v[110:113], v[138:141], v[34:49]
	ds_read_b64_tr_b16 v[138:139], v137 offset:0x2600
	ds_read_b64_tr_b16 v[140:141], v137 offset:0x2e00
	v_mfma_f32_32x32x16_bf16 v[34:49], v[122:125], v[142:145], v[34:49]
	ds_read_b64_tr_b16 v[142:143], v137 offset:0x3600
	ds_read_b64_tr_b16 v[144:145], v137 offset:0x3e00
	s_waitcnt lgkmcnt(0)
	v_mfma_f32_32x32x16_bf16 v[18:33], v[102:105], v[126:129], v[18:33]
	v_max_f32_e32 v97, v98, v99
	v_max3_f32 v97, v97, v100, v84
	v_max3_f32 v97, v97, v85, v86
	v_max3_f32 v97, v97, v87, v88
	v_max3_f32 v97, v97, v89, v90
	v_max3_f32 v97, v97, v91, v92
	v_mfma_f32_32x32x16_bf16 v[18:33], v[106:109], v[130:133], v[18:33]
	v_max3_f32 v97, v97, v93, v94
	v_max3_f32 v97, v97, v95, v96
	v_max3_f32 v97, v97, v82, v83
	v_max3_f32 v97, v97, v68, v69
	v_max3_f32 v97, v97, v70, v71
	v_max3_f32 v97, v97, v72, v73
	v_max3_f32 v97, v97, v74, v75
	v_max3_f32 v97, v97, v76, v77
	v_mfma_f32_32x32x16_bf16 v[18:33], v[110:113], v[138:141], v[18:33]
	v_max3_f32 v97, v97, v78, v79
	v_max3_f32 v97, v97, v80, v81
	v_mov_b32_e32 v101, v97
	s_nop 1
	v_permlane32_swap_b32_e32 v97, v101
	v_max_f32_e32 v97, v97, v101
	v_sub_f32_e32 v101, v97, v171
	v_cmp_ge_f32_e32 vcc, s58, v101
	v_mfma_f32_32x32x16_bf16 v[18:33], v[122:125], v[142:145], v[18:33]
	v_max_f32_e32 v101, v171, v97
	v_sub_f32_e32 v97, v171, v101
	v_exp_f32_e32 v97, v97
	s_cmp_eq_u64 vcc, exec
	s_cselect_b64 s[38:39], -1, 0
	v_cndmask_b32_e64 v97, v97, 1.0, s[38:39]
	v_cmp_gt_f32_e32 vcc, 1.0, v97
	s_barrier
	s_cbranch_vccz .LBB0_286
	s_and_saveexec_b64 s[4:5], s[36:37]
	ds_write_b32 v119, v97 offset:128
	s_or_b64 exec, exec, s[4:5]
	s_waitcnt lgkmcnt(0)
	v_add_u32_e32 v115, s22, v174
	ds_read_b128 v[102:105], v115 offset:224
	ds_read_b128 v[106:109], v115 offset:192
	ds_read_b128 v[110:113], v115 offset:160
	ds_read_b128 v[122:125], v115 offset:128
	s_waitcnt lgkmcnt(3)
	v_pk_mul_f32 v[14:15], v[14:15], v[102:103]
	s_waitcnt lgkmcnt(2)
	v_pk_mul_f32 v[10:11], v[10:11], v[106:107]
	s_waitcnt lgkmcnt(1)
	v_pk_mul_f32 v[6:7], v[6:7], v[110:111]
	v_pk_mul_f32 v[16:17], v[16:17], v[104:105]
	v_pk_mul_f32 v[12:13], v[12:13], v[108:109]
	v_pk_mul_f32 v[8:9], v[8:9], v[112:113]
	s_waitcnt lgkmcnt(0)
	v_pk_mul_f32 v[4:5], v[4:5], v[124:125]
	v_pk_mul_f32 v[2:3], v[2:3], v[122:123]
	v_pk_mul_f32 v[62:63], v[62:63], v[102:103]
	v_pk_mul_f32 v[58:59], v[58:59], v[106:107]
	v_pk_mul_f32 v[54:55], v[54:55], v[110:111]
	v_pk_mul_f32 v[64:65], v[64:65], v[104:105]
	v_pk_mul_f32 v[60:61], v[60:61], v[108:109]
	v_pk_mul_f32 v[56:57], v[56:57], v[112:113]
	v_pk_mul_f32 v[52:53], v[52:53], v[124:125]
	v_pk_mul_f32 v[50:51], v[50:51], v[122:123]
	v_pk_mul_f32 v[46:47], v[46:47], v[102:103]
	v_pk_mul_f32 v[42:43], v[42:43], v[106:107]
	v_pk_mul_f32 v[38:39], v[38:39], v[110:111]
	v_pk_mul_f32 v[48:49], v[48:49], v[104:105]
	v_pk_mul_f32 v[44:45], v[44:45], v[108:109]
	v_pk_mul_f32 v[40:41], v[40:41], v[112:113]
	v_pk_mul_f32 v[36:37], v[36:37], v[124:125]
	v_pk_mul_f32 v[34:35], v[34:35], v[122:123]
	v_pk_mul_f32 v[30:31], v[30:31], v[102:103]
	v_pk_mul_f32 v[26:27], v[26:27], v[106:107]
	v_pk_mul_f32 v[22:23], v[22:23], v[110:111]
	v_pk_mul_f32 v[32:33], v[32:33], v[104:105]
	v_pk_mul_f32 v[28:29], v[28:29], v[108:109]
	v_pk_mul_f32 v[24:25], v[24:25], v[112:113]
	v_pk_mul_f32 v[20:21], v[20:21], v[124:125]
	v_pk_mul_f32 v[18:19], v[18:19], v[122:123]
